# DPP/permlane butterflies extended to all row-wise LN phases and in-proj norm path; sub-LN phase issues both row loads before waiting
# baseline (speedup 1.0000x reference)
; __device__ __forceinline__ float shx(float v, int o) { const int l = lane_now(); return __int_as_float(__builtin_amdgcn_ds_bpermute((l ^ o) << 2, __float_as_int(v))); }
;     __device__ __forceinline__ void operator()(const f32x4 (&acc)[2][2][4][2], const Unit& u, int wr, int wc, int fr, int fq) const {
;     ...
;         if (pn < 4) {
;             float mx[2] = {0.f, 0.f};
; #pragma unroll
;             for (int ai = 0; ai < 2; ++ai)
; #pragma unroll
;                 for (int m = 0; m < 4; ++m)
; #pragma unroll
;                     for (int bj = 0; bj < 2; ++bj) { const f32x4 v0 = acc[ai][bj][m][0] * sc, v1 = acc[ai][bj][m][1] * sc;
;                         float ss = (v0[0] * v0[0] + v0[1] * v0[1]) + (v0[2] * v0[2] + v0[3] * v0[3]) + (v1[0] * v1[0] + v1[1] * v1[1]) + (v1[2] * v1[2] + v1[3] * v1[3]);
;                         ss += shx(ss, 16); ss += shx(ss, 32); mx[bj] = fmaxf(mx[bj], ss); }
.LBB0_296:
	v_mov_b32_e32 v139, v138
	v_pk_mul_f32 v[0:1], v[138:139], v[126:127]
	v_pk_mul_f32 v[4:5], v[138:139], v[122:123]
	v_mul_f32_e32 v122, v143, v143
	v_mul_f32_e32 v1, v1, v1
	v_fmac_f32_e32 v122, v142, v142
	v_fmac_f32_e32 v1, v0, v0
	v_add_f32_e32 v0, v122, v1
	v_mul_f32_e32 v1, v141, v141
	v_fmac_f32_e32 v1, v140, v140
	v_add_f32_e32 v0, v0, v1
	v_mul_f32_e32 v1, v5, v5
	v_fmac_f32_e32 v1, v4, v4
	v_add_f32_e32 v0, v1, v0
	v_pk_mul_f32 v[4:5], v[138:139], v[110:111]
	v_mov_b32_e32 v1, v0
	v_mov_b32_e32 v200, v0
	s_nop 1
	v_permlane16_swap_b32_e32 v1, v200
	v_cndmask_b32_e64 v1, v200, v1, s[98:99]
	v_mul_f32_e32 v110, v125, v125
	v_fmac_f32_e32 v110, v124, v124
	v_mul_f32_e32 v111, v5, v5
	v_fmac_f32_e32 v111, v4, v4
	v_add_f32_e32 v0, v0, v1
	v_pk_mul_f32 v[4:5], v[138:139], v[106:107]
	v_mov_b32_e32 v1, v0
	v_mov_b32_e32 v200, v0
	s_nop 1
	v_permlane32_swap_b32_e32 v1, v200
	v_cndmask_b32_e64 v1, v200, v1, s[100:101]
	v_mul_f32_e32 v106, v117, v117
	v_fmac_f32_e32 v106, v116, v116
	v_pk_mul_f32 v[90:91], v[138:139], v[90:91]
	v_pk_mul_f32 v[94:95], v[138:139], v[94:95]
	v_add_f32_e32 v122, v0, v1
	v_pk_mul_f32 v[0:1], v[138:139], v[118:119]
	v_mbcnt_lo_u32_b32 v118, -1, 0
	v_mbcnt_hi_u32_b32 v118, -1, v118
	v_mbcnt_lo_u32_b32 v119, -1, 0
	v_mbcnt_hi_u32_b32 v119, -1, v119
	v_mul_f32_e32 v95, v95, v95
	v_mul_f32_e32 v1, v1, v1
	v_fmac_f32_e32 v1, v0, v0
	v_add_f32_e32 v0, v110, v1
	v_mul_f32_e32 v1, v121, v121
	v_fmac_f32_e32 v1, v120, v120
	v_add_f32_e32 v110, v0, v1
	v_pk_mul_f32 v[0:1], v[138:139], v[114:115]
	v_fmac_f32_e32 v95, v94, v94
	v_mul_f32_e32 v1, v1, v1
	v_fmac_f32_e32 v1, v0, v0
	v_add_f32_e32 v0, v106, v1
	v_mul_f32_e32 v1, v109, v109
	v_fmac_f32_e32 v1, v108, v108
	v_add_f32_e32 v0, v0, v1
	v_mul_f32_e32 v1, v5, v5
	v_fmac_f32_e32 v1, v4, v4
	v_add_f32_e32 v0, v1, v0
	v_mov_b32_e32 v1, v0
	v_mov_b32_e32 v200, v0
	s_nop 1
	v_permlane16_swap_b32_e32 v1, v200
	v_cndmask_b32_e64 v1, v200, v1, s[98:99]
	v_add_f32_e32 v4, v111, v110
	v_mov_b32_e32 v5, v4
	v_mov_b32_e32 v200, v4
	s_nop 1
	v_permlane16_swap_b32_e32 v5, v200
	v_cndmask_b32_e64 v5, v200, v5, s[98:99]
	v_pk_mul_f32 v[86:87], v[138:139], v[86:87]
	v_add_f32_e32 v106, v0, v1
	v_mbcnt_lo_u32_b32 v94, -1, 0
	v_mbcnt_hi_u32_b32 v94, -1, v94
	v_mul_f32_e32 v87, v87, v87
	v_mov_b32_e32 v107, v106
	v_mov_b32_e32 v200, v106
	s_nop 1
	v_permlane32_swap_b32_e32 v107, v200
	v_cndmask_b32_e64 v107, v200, v107, s[100:101]
	v_add_f32_e32 v0, v4, v5
	v_fmac_f32_e32 v87, v86, v86
	v_pk_mul_f32 v[78:79], v[138:139], v[78:79]
	v_pk_mul_f32 v[74:75], v[138:139], v[74:75]
	v_add_f32_e32 v4, v106, v107
	v_max3_f32 v106, v122, 0, v4
	v_pk_mul_f32 v[4:5], v[138:139], v[102:103]
	v_mul_f32_e32 v102, v113, v113
	v_mul_f32_e32 v5, v5, v5
	v_fmac_f32_e32 v102, v112, v112
	v_fmac_f32_e32 v5, v4, v4
	v_add_f32_e32 v4, v102, v5
	v_mul_f32_e32 v5, v105, v105
	v_fmac_f32_e32 v5, v104, v104
	v_add_f32_e32 v102, v4, v5
	v_pk_mul_f32 v[4:5], v[138:139], v[98:99]
	v_mul_f32_e32 v98, v101, v101
	v_mul_f32_e32 v5, v5, v5
	v_fmac_f32_e32 v98, v100, v100
	v_fmac_f32_e32 v5, v4, v4
	v_add_f32_e32 v4, v98, v5
	v_mul_f32_e32 v5, v93, v93
	v_fmac_f32_e32 v5, v92, v92
	v_add_f32_e32 v4, v4, v5
	v_mul_f32_e32 v5, v91, v91
	v_fmac_f32_e32 v5, v90, v90
	v_mbcnt_lo_u32_b32 v103, -1, 0
	v_mbcnt_hi_u32_b32 v103, -1, v103
	v_add_f32_e32 v4, v5, v4
	v_mov_b32_e32 v5, v4
	v_mov_b32_e32 v200, v4
	s_nop 1
	v_permlane16_swap_b32_e32 v5, v200
	v_cndmask_b32_e64 v5, v200, v5, s[98:99]
	v_add_f32_e32 v90, v95, v102
	v_mov_b32_e32 v91, v90
	v_mov_b32_e32 v200, v90
	s_nop 1
	v_permlane16_swap_b32_e32 v91, v200
	v_cndmask_b32_e64 v91, v200, v91, s[98:99]
	v_mul_f32_e32 v77, v77, v77
	v_add_f32_e32 v92, v4, v5
	v_fmac_f32_e32 v77, v76, v76
	v_mov_b32_e32 v93, v92
	v_mov_b32_e32 v200, v92
	s_nop 1
	v_permlane32_swap_b32_e32 v93, v200
	v_cndmask_b32_e64 v93, v200, v93, s[100:101]
	v_add_f32_e32 v4, v90, v91
	v_mul_f32_e32 v91, v97, v97
	v_fmac_f32_e32 v91, v96, v96
	v_add_f32_e32 v86, v91, v87
	v_mul_f32_e32 v87, v89, v89
	v_fmac_f32_e32 v87, v88, v88
	v_add_f32_e32 v86, v86, v87
	v_mul_f32_e32 v87, v79, v79
	v_fmac_f32_e32 v87, v78, v78
	v_pk_mul_f32 v[78:79], v[138:139], v[82:83]
	v_mul_f32_e32 v82, v85, v85
	v_mul_f32_e32 v79, v79, v79
	v_fmac_f32_e32 v82, v84, v84
	v_fmac_f32_e32 v79, v78, v78
	v_add_f32_e32 v78, v82, v79
	v_mul_f32_e32 v75, v75, v75
	v_add_f32_e32 v76, v78, v77
	v_fmac_f32_e32 v75, v74, v74
	v_mbcnt_lo_u32_b32 v88, -1, 0
	v_mbcnt_hi_u32_b32 v88, -1, v88
	v_mbcnt_lo_u32_b32 v89, -1, 0
	v_mbcnt_hi_u32_b32 v89, -1, v89
	v_add_f32_e32 v74, v75, v76
	v_mov_b32_e32 v75, v74
	v_mov_b32_e32 v200, v74
	s_nop 1
	v_permlane16_swap_b32_e32 v75, v200
	v_cndmask_b32_e64 v75, v200, v75, s[98:99]
	v_add_f32_e32 v76, v87, v86
	v_mov_b32_e32 v77, v76
	v_mov_b32_e32 v200, v76
	s_nop 1
	v_permlane16_swap_b32_e32 v77, v200
	v_cndmask_b32_e64 v77, v200, v77, s[98:99]
	v_pk_mul_f32 v[62:63], v[138:139], v[62:63]
	v_add_f32_e32 v78, v74, v75
	v_pk_mul_f32 v[70:71], v[138:139], v[70:71]
	v_mul_f32_e32 v69, v69, v69
	v_mul_f32_e32 v63, v63, v63
	v_mov_b32_e32 v79, v78
	v_mov_b32_e32 v200, v78
	s_nop 1
	v_permlane32_swap_b32_e32 v79, v200
	v_cndmask_b32_e64 v79, v200, v79, s[100:101]
	v_add_f32_e32 v74, v76, v77
	v_mul_f32_e32 v77, v81, v81
	v_mul_f32_e32 v71, v71, v71
	v_fmac_f32_e32 v69, v68, v68
	v_fmac_f32_e32 v63, v62, v62
	v_fmac_f32_e32 v77, v80, v80
	v_fmac_f32_e32 v71, v70, v70
	v_pk_mul_f32 v[58:59], v[138:139], v[58:59]
	v_add_f32_e32 v62, v69, v63
	v_mul_f32_e32 v63, v65, v65
	v_pk_mul_f32 v[54:55], v[138:139], v[54:55]
	v_pk_mul_f32 v[66:67], v[138:139], v[66:67]
	v_add_f32_e32 v70, v77, v71
	v_mul_f32_e32 v71, v73, v73
; __device__ __forceinline__ float shx(float v, int o) { const int l = lane_now(); return __int_as_float(__builtin_amdgcn_ds_bpermute((l ^ o) << 2, __float_as_int(v))); }
;     __device__ __forceinline__ void operator()(const f32x4 (&acc)[2][2][4][2], const Unit& u, int wr, int wc, int fr, int fq) const {
;     ...
;                     for (int bj = 0; bj < 2; ++bj) { const f32x4 v0 = acc[ai][bj][m][0] * sc, v1 = acc[ai][bj][m][1] * sc;
;                         float ss = (v0[0] * v0[0] + v0[1] * v0[1]) + (v0[2] * v0[2] + v0[3] * v0[3]) + (v1[0] * v1[0] + v1[1] * v1[1]) + (v1[2] * v1[2] + v1[3] * v1[3]);
;                         ss += shx(ss, 16); ss += shx(ss, 32); mx[bj] = fmaxf(mx[bj], ss); }
	v_fmac_f32_e32 v63, v64, v64
	v_mul_f32_e32 v59, v59, v59
	v_mul_f32_e32 v61, v61, v61
	v_mul_f32_e32 v55, v55, v55
	v_fmac_f32_e32 v71, v72, v72
	v_mul_f32_e32 v67, v67, v67
	v_add_f32_e32 v62, v62, v63
	v_fmac_f32_e32 v59, v58, v58
	v_fmac_f32_e32 v61, v60, v60
	v_fmac_f32_e32 v55, v54, v54
	v_add_f32_e32 v70, v70, v71
	v_fmac_f32_e32 v67, v66, v66
	v_mbcnt_lo_u32_b32 v66, -1, 0
	v_mbcnt_hi_u32_b32 v66, -1, v66
	v_mbcnt_lo_u32_b32 v71, -1, 0
	v_mbcnt_hi_u32_b32 v71, -1, v71
	v_add_f32_e32 v58, v59, v62
	v_add_f32_e32 v54, v61, v55
	v_mul_f32_e32 v55, v57, v57
	v_pk_mul_f32 v[46:47], v[138:139], v[46:47]
	v_fmac_f32_e32 v55, v56, v56
	v_add_f32_e32 v54, v54, v55
	v_mul_f32_e32 v55, v47, v47
	v_mov_b32_e32 v59, v58
	v_mov_b32_e32 v200, v58
	s_nop 1
	v_permlane16_swap_b32_e32 v59, v200
	v_cndmask_b32_e64 v59, v200, v59, s[98:99]
	v_fmac_f32_e32 v55, v46, v46
	v_pk_mul_f32 v[46:47], v[138:139], v[50:51]
	v_mul_f32_e32 v50, v53, v53
	v_mul_f32_e32 v47, v47, v47
	v_pk_mul_f32 v[42:43], v[138:139], v[42:43]
	v_fmac_f32_e32 v50, v52, v52
	v_fmac_f32_e32 v47, v46, v46
	v_mul_f32_e32 v45, v45, v45
	v_add_f32_e32 v46, v50, v47
	v_fmac_f32_e32 v45, v44, v44
	v_mul_f32_e32 v43, v43, v43
	v_add_f32_e32 v44, v46, v45
	v_fmac_f32_e32 v43, v42, v42
	v_add_f32_e32 v64, v58, v59
	v_mbcnt_lo_u32_b32 v56, -1, 0
	v_mbcnt_hi_u32_b32 v56, -1, v56
	v_mbcnt_lo_u32_b32 v57, -1, 0
	v_mbcnt_hi_u32_b32 v57, -1, v57
	v_add_f32_e32 v42, v43, v44
	v_mov_b32_e32 v43, v42
	v_mov_b32_e32 v200, v42
	s_nop 1
	v_permlane16_swap_b32_e32 v43, v200
	v_cndmask_b32_e64 v43, v200, v43, s[98:99]
	v_add_f32_e32 v44, v55, v54
	v_mov_b32_e32 v45, v44
	v_mov_b32_e32 v200, v44
	s_nop 1
	v_permlane16_swap_b32_e32 v45, v200
	v_cndmask_b32_e64 v45, v200, v45, s[98:99]
	v_pk_mul_f32 v[38:39], v[138:139], v[38:39]
	v_add_f32_e32 v46, v42, v43
	v_mul_f32_e32 v39, v39, v39
	v_mov_b32_e32 v47, v46
	v_mov_b32_e32 v200, v46
	s_nop 1
	v_permlane32_swap_b32_e32 v47, v200
	v_cndmask_b32_e64 v47, v200, v47, s[100:101]
	v_add_f32_e32 v42, v44, v45
	v_mul_f32_e32 v45, v49, v49
	v_pk_mul_f32 v[30:31], v[138:139], v[30:31]
	v_fmac_f32_e32 v45, v48, v48
	v_fmac_f32_e32 v39, v38, v38
	v_add_f32_e32 v38, v45, v39
	v_mul_f32_e32 v39, v41, v41
	v_mul_f32_e32 v31, v31, v31
	v_fmac_f32_e32 v39, v40, v40
	v_fmac_f32_e32 v31, v30, v30
	v_add_f32_e32 v38, v38, v39
	v_add_f32_e32 v38, v31, v38
	v_mov_b32_e32 v39, v38
	v_mov_b32_e32 v200, v38
	s_nop 1
	v_permlane16_swap_b32_e32 v39, v200
	v_cndmask_b32_e64 v39, v200, v39, s[98:99]
	v_pk_mul_f32 v[30:31], v[138:139], v[34:35]
	v_mul_f32_e32 v34, v37, v37
	v_mul_f32_e32 v31, v31, v31
	v_fmac_f32_e32 v34, v36, v36
	v_fmac_f32_e32 v31, v30, v30
	v_mul_f32_e32 v29, v29, v29
	v_add_f32_e32 v30, v34, v31
	v_fmac_f32_e32 v29, v28, v28
	v_pk_mul_f32 v[22:23], v[138:139], v[22:23]
	v_pk_mul_f32 v[26:27], v[138:139], v[26:27]
	v_add_f32_e32 v28, v30, v29
	v_mul_f32_e32 v30, v33, v33
	v_mul_f32_e32 v23, v23, v23
	v_mul_f32_e32 v27, v27, v27
	v_fmac_f32_e32 v30, v32, v32
	v_fmac_f32_e32 v23, v22, v22
	v_mbcnt_lo_u32_b32 v40, -1, 0
	v_mbcnt_hi_u32_b32 v40, -1, v40
	v_fmac_f32_e32 v27, v26, v26
	v_add_f32_e32 v22, v30, v23
	v_mul_f32_e32 v23, v25, v25
	v_pk_mul_f32 v[14:15], v[138:139], v[14:15]
	v_fmac_f32_e32 v23, v24, v24
	v_add_f32_e32 v28, v27, v28
	v_add_f32_e32 v22, v22, v23
	v_mul_f32_e32 v23, v15, v15
	v_mov_b32_e32 v29, v28
	v_mov_b32_e32 v200, v28
	s_nop 1
	v_permlane16_swap_b32_e32 v29, v200
	v_cndmask_b32_e64 v29, v200, v29, s[98:99]
	v_fmac_f32_e32 v23, v14, v14
	v_pk_mul_f32 v[14:15], v[138:139], v[18:19]
	v_mul_f32_e32 v18, v21, v21
	v_mul_f32_e32 v15, v15, v15
	v_pk_mul_f32 v[10:11], v[138:139], v[10:11]
	v_fmac_f32_e32 v18, v20, v20
	v_fmac_f32_e32 v15, v14, v14
	v_mul_f32_e32 v13, v13, v13
	v_add_f32_e32 v14, v18, v15
	v_fmac_f32_e32 v13, v12, v12
	v_mul_f32_e32 v11, v11, v11
	v_add_f32_e32 v12, v14, v13
	v_fmac_f32_e32 v11, v10, v10
	v_add_f32_e32 v28, v28, v29
	v_mbcnt_lo_u32_b32 v24, -1, 0
	v_mbcnt_hi_u32_b32 v24, -1, v24
; __device__ __forceinline__ float shx(float v, int o) { const int l = lane_now(); return __int_as_float(__builtin_amdgcn_ds_bpermute((l ^ o) << 2, __float_as_int(v))); }
;     __device__ __forceinline__ void operator()(const f32x4 (&acc)[2][2][4][2], const Unit& u, int wr, int wc, int fr, int fq) const {
;     ...
;                     for (int bj = 0; bj < 2; ++bj) { const f32x4 v0 = acc[ai][bj][m][0] * sc, v1 = acc[ai][bj][m][1] * sc;
;                         float ss = (v0[0] * v0[0] + v0[1] * v0[1]) + (v0[2] * v0[2] + v0[3] * v0[3]) + (v1[0] * v1[0] + v1[1] * v1[1]) + (v1[2] * v1[2] + v1[3] * v1[3]);
;                         ss += shx(ss, 16); ss += shx(ss, 32); mx[bj] = fmaxf(mx[bj], ss); }
; #pragma unroll
;             for (int bj = 0; bj < 2; ++bj) { float v = mx[bj]; v = fmaxf(v, shx(v, 1)); v = fmaxf(v, shx(v, 2)); v = fmaxf(v, shx(v, 4)); v = fmaxf(v, shx(v, 8));
;                 if (fr == 0 && fq == 0) atomicMax(nrm + (pn >> 1) * 16 + (4 * (pn & 1) + 2 * bj + (wc >> 1)) * 2 + (wc & 1), __float_as_uint(v)); }
	v_mbcnt_lo_u32_b32 v25, -1, 0
	v_mbcnt_hi_u32_b32 v25, -1, v25
	v_add_f32_e32 v10, v11, v12
	v_mov_b32_e32 v11, v10
	v_mov_b32_e32 v200, v10
	s_nop 1
	v_permlane16_swap_b32_e32 v11, v200
	v_cndmask_b32_e64 v11, v200, v11, s[98:99]
	v_add_f32_e32 v12, v23, v22
	v_mov_b32_e32 v13, v12
	v_mov_b32_e32 v200, v12
	s_nop 1
	v_permlane16_swap_b32_e32 v13, v200
	v_cndmask_b32_e64 v13, v200, v13, s[98:99]
	v_add_f32_e32 v11, v10, v11
	v_add_f32_e32 v62, v67, v70
	v_mov_b32_e32 v63, v62
	v_mov_b32_e32 v200, v62
	s_nop 1
	v_permlane16_swap_b32_e32 v63, v200
	v_cndmask_b32_e64 v63, v200, v63, s[98:99]
	v_mov_b32_e32 v65, v64
	v_mov_b32_e32 v200, v64
	s_nop 1
	v_permlane32_swap_b32_e32 v65, v200
	v_cndmask_b32_e64 v65, v200, v65, s[100:101]
	v_pk_mul_f32 v[6:7], v[138:139], v[6:7]
	v_mov_b32_e32 v29, v28
	v_mov_b32_e32 v200, v28
	s_nop 1
	v_permlane32_swap_b32_e32 v29, v200
	v_cndmask_b32_e64 v29, v200, v29, s[100:101]
	v_mov_b32_e32 v14, v11
	v_mov_b32_e32 v200, v11
	s_nop 1
	v_permlane32_swap_b32_e32 v14, v200
	v_cndmask_b32_e64 v14, v200, v14, s[100:101]
	v_add_f32_e32 v10, v12, v13
	v_mul_f32_e32 v13, v17, v17
	v_mul_f32_e32 v7, v7, v7
	v_fmac_f32_e32 v13, v16, v16
	v_fmac_f32_e32 v7, v6, v6
	v_pk_mul_f32 v[2:3], v[138:139], v[2:3]
	v_add_f32_e32 v6, v13, v7
	v_mul_f32_e32 v7, v9, v9
	v_add_f32_e32 v90, v92, v93
	v_add_f32_e32 v76, v78, v79
	v_fmac_f32_e32 v7, v8, v8
	v_mul_f32_e32 v3, v3, v3
	v_max3_f32 v76, v106, v90, v76
	v_add_f32_e32 v58, v62, v63
	v_add_f32_e32 v62, v64, v65
	v_add_f32_e32 v44, v46, v47
	v_add_f32_e32 v6, v6, v7
	v_fmac_f32_e32 v3, v2, v2
	v_max3_f32 v44, v76, v62, v44
	v_add_f32_e32 v15, v28, v29
	v_add_f32_e32 v11, v11, v14
	v_max3_f32 v11, v44, v15, v11
	s_nop 1
	v_mov_b32_dpp v8, v11 quad_perm:[1,0,3,2] row_mask:0xf bank_mask:0xf
	v_add_f32_e32 v3, v3, v6
	v_mov_b32_e32 v6, v3
	v_mov_b32_e32 v200, v3
	s_nop 1
	v_permlane16_swap_b32_e32 v6, v200
	v_cndmask_b32_e64 v6, v200, v6, s[98:99]
	v_max_f32_e32 v2, v8, v8
	v_max_f32_e32 v8, v11, v2
	s_nop 1
	v_mov_b32_dpp v9, v8 quad_perm:[2,3,0,1] row_mask:0xf bank_mask:0xf
	v_add_f32_e32 v3, v3, v6
	v_max_f32_e32 v7, v9, v9
	v_max_f32_e32 v7, v8, v7
	s_nop 1
	v_mov_b32_dpp v8, v7 row_shl:4 row_mask:0xf bank_mask:0x5
	v_mov_b32_dpp v8, v7 row_shr:4 row_mask:0xf bank_mask:0xa
	v_lshlrev_b32_e32 v12, 2, v25
	v_max_f32_e32 v8, v8, v8
	v_max_f32_e32 v7, v7, v8
	v_add_f32_e32 v26, v38, v39
	v_xor_b32_e32 v12, 0x80, v12
	v_mov_b32_e32 v1, v0
	v_mov_b32_e32 v200, v0
	s_nop 1
	v_permlane32_swap_b32_e32 v1, v200
	v_cndmask_b32_e64 v1, v200, v1, s[100:101]
	v_mov_b32_e32 v5, v4
	v_mov_b32_e32 v200, v4
	s_nop 1
	v_permlane32_swap_b32_e32 v5, v200
	v_cndmask_b32_e64 v5, v200, v5, s[100:101]
	v_mov_b32_e32 v75, v74
	v_mov_b32_e32 v200, v74
	s_nop 1
	v_permlane32_swap_b32_e32 v75, v200
	v_cndmask_b32_e64 v75, v200, v75, s[100:101]
	v_mov_b32_e32 v59, v58
	v_mov_b32_e32 v200, v58
	s_nop 1
	v_permlane32_swap_b32_e32 v59, v200
	v_cndmask_b32_e64 v59, v200, v59, s[100:101]
	v_mov_b32_e32 v43, v42
	v_mov_b32_e32 v200, v42
	s_nop 1
	v_permlane32_swap_b32_e32 v43, v200
	v_cndmask_b32_e64 v43, v200, v43, s[100:101]
	v_mov_b32_e32 v27, v26
	v_mov_b32_e32 v200, v26
	s_nop 1
	v_permlane32_swap_b32_e32 v27, v200
	v_cndmask_b32_e64 v27, v200, v27, s[100:101]
	v_mov_b32_e32 v2, v10
	v_mov_b32_e32 v200, v10
	s_nop 1
	v_permlane32_swap_b32_e32 v2, v200
	v_cndmask_b32_e64 v2, v200, v2, s[100:101]
	v_mov_b32_e32 v6, v3
	v_mov_b32_e32 v200, v3
	s_nop 1
	v_permlane32_swap_b32_e32 v6, v200
	v_cndmask_b32_e64 v6, v200, v6, s[100:101]
	s_nop 1
	v_mov_b32_dpp v8, v7 row_ror:8 row_mask:0xf bank_mask:0xf
	s_lshl_b32 s6, s59, 3
	v_or_b32_e32 v9, v163, v162
	s_lshl_b32 s10, s18, 4
	s_and_b32 s6, s6, 8
	v_cmp_eq_u32_e32 vcc, 0, v9
	s_ashr_i32 s11, s10, 31
	s_or_b32 s24, s6, s77
	s_and_saveexec_b64 s[18:19], vcc
	s_cbranch_execz .LBB0_301
	v_max_f32_e32 v8, v8, v8
	v_max_f32_e32 v7, v7, v7
	s_mov_b64 s[6:7], exec
	v_max_f32_e32 v7, v7, v8
	s_mov_b32 s40, 0

; __device__ __forceinline__ float shx(float v, int o) { const int l = lane_now(); return __int_as_float(__builtin_amdgcn_ds_bpermute((l ^ o) << 2, __float_as_int(v))); }
;     __device__ __forceinline__ void operator()(const f32x4 (&acc)[2][2][4][2], const Unit& u, int wr, int wc, int fr, int fq) const {
;     ...
;             for (int bj = 0; bj < 2; ++bj) { float v = mx[bj]; v = fmaxf(v, shx(v, 1)); v = fmaxf(v, shx(v, 2)); v = fmaxf(v, shx(v, 4)); v = fmaxf(v, shx(v, 8));
;                 if (fr == 0 && fq == 0) atomicMax(nrm + (pn >> 1) * 16 + (4 * (pn & 1) + 2 * bj + (wc >> 1)) * 2 + (wc & 1), __float_as_uint(v)); }
.LBB0_301:
	s_or_b64 exec, exec, s[18:19]
	s_waitcnt lgkmcnt(8)
	v_add_f32_e32 v0, v0, v1
	s_waitcnt lgkmcnt(7)
	v_add_f32_e32 v1, v4, v5
	v_max3_f32 v0, v0, 0, v1
	s_waitcnt lgkmcnt(6)
	v_add_f32_e32 v1, v74, v75
	s_waitcnt lgkmcnt(5)
	v_add_f32_e32 v4, v58, v59
	v_max3_f32 v0, v0, v1, v4
	s_waitcnt lgkmcnt(4)
	v_add_f32_e32 v1, v42, v43
	s_waitcnt lgkmcnt(3)
	v_add_f32_e32 v4, v26, v27
	v_max3_f32 v0, v0, v1, v4
	s_waitcnt lgkmcnt(2)
	v_add_f32_e32 v1, v10, v2
	s_waitcnt lgkmcnt(1)
	v_add_f32_e32 v2, v3, v6
	v_max3_f32 v0, v0, v1, v2
	s_nop 0
	s_nop 1
	v_mov_b32_dpp v1, v0 quad_perm:[1,0,3,2] row_mask:0xf bank_mask:0xf
	v_max_f32_e32 v1, v1, v1
	v_max_f32_e32 v0, v0, v1
	s_nop 0
	s_nop 1
	v_mov_b32_dpp v1, v0 quad_perm:[2,3,0,1] row_mask:0xf bank_mask:0xf
	v_max_f32_e32 v1, v1, v1
	v_max_f32_e32 v0, v0, v1
	s_nop 0
	s_nop 1
	v_mov_b32_dpp v1, v0 row_shl:4 row_mask:0xf bank_mask:0x5
	v_mov_b32_dpp v1, v0 row_shr:4 row_mask:0xf bank_mask:0xa
	v_max_f32_e32 v1, v1, v1
	v_max_f32_e32 v0, v0, v1
	s_nop 0
	s_nop 1
	v_mov_b32_dpp v1, v0 row_ror:8 row_mask:0xf bank_mask:0xf
	s_and_saveexec_b64 s[6:7], vcc
	s_cbranch_execz .LBB0_306
	v_max_f32_e32 v1, v1, v1
	v_max_f32_e32 v0, v0, v0
	s_mov_b64 s[18:19], exec
	v_max_f32_e32 v0, v0, v1
	s_mov_b32 s40, 0

; __device__ __forceinline__ float shx(float v, int o) { const int l = lane_now(); return __int_as_float(__builtin_amdgcn_ds_bpermute((l ^ o) << 2, __float_as_int(v))); }
; #define in KArgIn()
; #define FRESH_IDS() const int tid = tid_fresh(wv), lane = tid & 63, wave = wv
; __device__ __forceinline__ float wave_sum(float v) {
; #pragma unroll
;     for (int o = 1; o < 64; o <<= 1) v += shx(v, o);
;     return v;
; }
; template <int l, int SEL> __device__ __forceinline__ void layer_body(const Args& args, LAS unsigned char* ldsp, unsigned char* lds, const int G, const int bx, const int vcu, const int wv) {
;     ...
;             FRESH_IDS();
;             const float lam_init = 0.8f - 0.6f * expf(-0.3f * (float)l);
;             const float a1 = wave_sum(in[5][l * 64 + lane] * in[6][l * 64 + lane]), a2 = wave_sum(in[7][l * 64 + lane] * in[8][l * 64 + lane]);
;             const float lam = expf(a1) - expf(a2) + lam_init;
;             const float* sg = in[9] + l * 128 + (lane & 15) * 8; float gsc[8];
; #pragma unroll
;             for (int i = 0; i < 8; ++i) gsc[i] = sg[i] * (1.f - lam_init);
.LBB0_596:
	s_or_b64 exec, exec, s[4:5]
	s_mov_b64 s[4:5], s[0:1]
	s_waitcnt lgkmcnt(0)
	s_barrier
	v_mbcnt_lo_u32_b32 v0, -1, 0
	v_mbcnt_hi_u32_b32 v0, -1, v0
	s_load_dwordx2 s[4:5], s[4:5], 0x28
	v_and_b32_e32 v2, 63, v0
	v_lshlrev_b32_e32 v1, 2, v2
	s_and_b64 vcc, exec, s[38:39]
	s_waitcnt lgkmcnt(0)
	global_load_dword v3, v1, s[4:5]
	s_mov_b64 s[4:5], s[0:1]
	s_load_dwordx2 s[4:5], s[4:5], 0x30
	s_waitcnt lgkmcnt(0)
	global_load_dword v4, v1, s[4:5]
	s_mov_b64 s[4:5], s[0:1]
	s_load_dwordx2 s[4:5], s[4:5], 0x38
	s_waitcnt lgkmcnt(0)
	global_load_dword v11, v1, s[4:5]
	s_mov_b64 s[4:5], s[0:1]
	s_load_dwordx2 s[4:5], s[4:5], 0x40
	s_waitcnt lgkmcnt(0)
	global_load_dword v1, v1, s[4:5]
	s_mov_b64 s[4:5], s[0:1]
	s_waitcnt vmcnt(2)
	v_mul_f32_e32 v18, v3, v4
	s_nop 1
	v_mov_b32_dpp v5, v18 quad_perm:[1,0,3,2] row_mask:0xf bank_mask:0xf
	v_fmac_f32_e32 v5, v3, v4
	s_nop 1
	v_mov_b32_dpp v3, v5 quad_perm:[2,3,0,1] row_mask:0xf bank_mask:0xf
	v_add_f32_e32 v3, v5, v3
	s_nop 1
	v_mov_b32_dpp v5, v3 row_shl:4 row_mask:0xf bank_mask:0x5
	v_mov_b32_dpp v5, v3 row_shr:4 row_mask:0xf bank_mask:0xa
	v_add_f32_e32 v3, v3, v5
	s_nop 1
	v_mov_b32_dpp v5, v3 row_ror:8 row_mask:0xf bank_mask:0xf
	s_waitcnt vmcnt(0)
	v_mul_f32_e32 v18, v11, v1
	s_nop 1
	v_mov_b32_dpp v12, v18 quad_perm:[1,0,3,2] row_mask:0xf bank_mask:0xf
	v_add_f32_e32 v3, v3, v5
	v_mov_b32_e32 v5, v3
	v_mov_b32_e32 v120, v3
	s_nop 1
	v_permlane16_swap_b32_e32 v5, v120
	v_cndmask_b32_e64 v5, v120, v5, s[98:99]
	v_fmac_f32_e32 v12, v11, v1
	s_nop 1
	v_mov_b32_dpp v1, v12 quad_perm:[2,3,0,1] row_mask:0xf bank_mask:0xf
	v_add_f32_e32 v1, v12, v1
	s_nop 1
	v_mov_b32_dpp v4, v1 row_shl:4 row_mask:0xf bank_mask:0x5
	v_mov_b32_dpp v4, v1 row_shr:4 row_mask:0xf bank_mask:0xa
	v_add_f32_e32 v1, v1, v4
	s_nop 1
	v_mov_b32_dpp v4, v1 row_ror:8 row_mask:0xf bank_mask:0xf
	v_add_f32_e32 v1, v1, v4
	v_mov_b32_e32 v6, v1
	v_mov_b32_e32 v120, v1
	s_nop 1
	v_permlane16_swap_b32_e32 v6, v120
	v_cndmask_b32_e64 v6, v120, v6, s[98:99]
	v_add_f32_e32 v4, v3, v5
	v_mov_b32_e32 v5, v4
	v_mov_b32_e32 v120, v4
	s_nop 1
	v_permlane32_swap_b32_e32 v5, v120
	v_cndmask_b32_e64 v5, v120, v5, s[100:101]
	v_add_f32_e32 v1, v1, v6
	v_mov_b32_e32 v3, v1
	v_mov_b32_e32 v120, v1
	s_nop 1
	v_permlane32_swap_b32_e32 v3, v120
	v_cndmask_b32_e64 v3, v120, v3, s[100:101]
	s_cbranch_vccz .LBB0_599
	s_load_dwordx2 s[4:5], s[4:5], 0x48
	v_lshlrev_b32_e32 v0, 5, v0
	v_and_b32_e32 v0, 0x1e0, v0
	s_waitcnt lgkmcnt(0)
	v_add_f32_e32 v4, v4, v5
	v_add_f32_e32 v16, v1, v3
	global_load_dwordx4 v[6:9], v0, s[4:5]
	global_load_dwordx4 v[10:13], v0, s[4:5] offset:16
	s_mov_b32 s5, 0x3fb8aa3b
	v_mul_f32_e32 v3, 0x3fb8aa3b, v4
	v_mul_f32_e32 v17, 0x3fb8aa3b, v16
	v_fma_f32 v18, v4, s5, -v3
	v_rndne_f32_e32 v19, v3
	v_fma_f32 v20, v16, s5, -v17
	v_rndne_f32_e32 v21, v17
	v_fmac_f32_e32 v18, 0x32a5705f, v4
	v_sub_f32_e32 v3, v3, v19
	v_fmac_f32_e32 v20, 0x32a5705f, v16
	v_sub_f32_e32 v17, v17, v21
	v_add_f32_e32 v3, v3, v18
	v_cvt_i32_f32_e32 v19, v19
	v_add_f32_e32 v17, v17, v20
	v_exp_f32_e32 v18, v3
	v_cvt_i32_f32_e32 v21, v21
	v_exp_f32_e32 v17, v17
	s_mov_b32 s17, 0xc2ce8ed0
	v_ldexp_f32 v18, v18, v19
	v_cmp_ngt_f32_e32 vcc, s17, v4
	s_mov_b32 s18, 0x42b17218
	v_ldexp_f32 v17, v17, v21
	v_cndmask_b32_e32 v18, 0, v18, vcc
	v_cmp_ngt_f32_e32 vcc, s17, v16
	v_mov_b32_e32 v5, 0x7f800000
	s_ashr_i32 s35, s34, 31
	v_cndmask_b32_e32 v17, 0, v17, vcc
	v_cmp_nlt_f32_e32 vcc, s18, v4
	s_lshl_b64 s[12:13], s[34:35], 10
	s_mov_b32 s4, 0x3f4ccccd
	v_cndmask_b32_e32 v4, v5, v18, vcc
	v_cmp_nlt_f32_e32 vcc, s18, v16
	v_lshlrev_b32_e32 v0, 3, v2
	s_mov_b64 s[10:11], 0x20500000
	v_cndmask_b32_e32 v5, v5, v17, vcc
	v_sub_f32_e32 v4, v4, v5
	s_ashr_i32 s31, s30, 31
	v_lshl_or_b32 v2, v2, 4, s12
	v_mov_b32_e32 v3, s13
	v_add_f32_e32 v4, 0x3e4ccccc, v4
	v_mov_b32_e32 v1, 0
	s_mov_b32 s3, 0x20500000
	s_mov_b32 s14, 0xffff0000
	v_mov_b32_e32 v14, 0x3727c5ac
	s_mov_b32 s15, 0xf800000
	v_mov_b32_e32 v15, 0x260
	s_movk_i32 s16, 0x7fff
	s_lshl_b64 s[6:7], s[30:31], 10
	v_lshlrev_b32_e32 v0, 1, v0
	v_lshl_add_u64 v[2:3], v[2:3], 0, s[10:11]
	v_mov_b32_e32 v5, v4
	s_mov_b32 s17, s34
	s_waitcnt vmcnt(1)
	v_mov_b32_e32 v16, v6
	v_mov_b32_e32 v17, v8
	v_mov_b32_e32 v8, v7
	s_waitcnt vmcnt(0)
	v_mov_b32_e32 v18, v10
	v_mov_b32_e32 v19, v12
	v_mov_b32_e32 v12, v11
	v_pk_mul_f32 v[6:7], v[16:17], s[4:5] op_sel_hi:[1,0]
	v_pk_mul_f32 v[8:9], v[8:9], s[4:5] op_sel_hi:[1,0]
	v_pk_mul_f32 v[10:11], v[18:19], s[4:5] op_sel_hi:[1,0]
	v_pk_mul_f32 v[12:13], v[12:13], s[4:5] op_sel_hi:[1,0]
; __device__ __forceinline__ float shx(float v, int o) { const int l = lane_now(); return __int_as_float(__builtin_amdgcn_ds_bpermute((l ^ o) << 2, __float_as_int(v))); }
; __device__ __forceinline__ float bf_lo(unsigned w) { return __uint_as_float(w << 16); }
; __device__ __forceinline__ float bf_hi(unsigned w) { return __uint_as_float(w & 0xffff0000u); }
; __device__ __forceinline__ unsigned pk2(float lo, float hi) { return f2bf(lo) | (f2bf(hi) << 16); }
; template <int l, int SEL> __device__ __forceinline__ void layer_body(const Args& args, LAS unsigned char* ldsp, unsigned char* lds, const int G, const int bx, const int vcu, const int wv) {
;     ...
;             for (int row = gw; row < M; row += NGW) {
;                 const v4u a = *(const v4u*)(q_odiff + (size_t)row * 512 + 8 * lane), b = *(const v4u*)(q_odiff + (size_t)(M + row) * 512 + 8 * lane);
;                 float o[8]; const unsigned aw[4] = {a.x, a.y, a.z, a.w}, bw[4] = {b.x, b.y, b.z, b.w};
; #pragma unroll
;                 for (int i = 0; i < 4; ++i) { o[2 * i] = pg8::bf_lo(aw[i]) - lam * pg8::bf_lo(bw[i]); o[2 * i + 1] = pg8::bf_hi(aw[i]) - lam * pg8::bf_hi(bw[i]); }
;                 float ss = 0.f;
; #pragma unroll
;                 for (int i = 0; i < 8; ++i) ss += o[i] * o[i];
;                 ss += shx(ss, 1); ss += shx(ss, 2); ss += shx(ss, 4); ss += shx(ss, 8);
;                 const float r = 1.f / sqrtf(ss * (1.f / 128.f) + SUBLN_EPS);
;                 v4u w; w.x = pk2(o[0] * r * gsc[0], o[1] * r * gsc[1]); w.y = pk2(o[2] * r * gsc[2], o[3] * r * gsc[3]); w.z = pk2(o[4] * r * gsc[4], o[5] * r * gsc[5]); w.w = pk2(o[6] * r * gsc[6], o[7] * r * gsc[7]);
;                 *(v4u*)(q_yatt + (size_t)(M + row) * 512 + 8 * lane) = w;
;             }
.LBB0_598:
	s_mov_b64 s[10:11], s[0:1]
	s_load_dwordx2 s[10:11], s[10:11], 0xc0
	s_mov_b64 s[4:5], s[0:1]
	s_add_i32 s12, s17, 0x4000
	s_ashr_i32 s13, s12, 31
	s_lshl_b64 s[12:13], s[12:13], 10
	s_waitcnt lgkmcnt(0)
	v_lshl_add_u64 v[16:17], s[10:11], 0, v[2:3]
	global_load_dwordx4 v[16:19], v[16:17], off
	s_load_dwordx2 s[4:5], s[4:5], 0xc0
	s_mov_b64 s[18:19], s[0:1]
	v_lshl_add_u64 v[2:3], v[2:3], 0, s[6:7]
	s_waitcnt lgkmcnt(0)
	s_add_u32 s4, s4, s12
	s_addc_u32 s5, s5, s13
	v_lshl_add_u64 v[20:21], s[4:5], 0, v[0:1]
	v_add_co_u32_e32 v20, vcc, s3, v20
	s_nop 1
	v_addc_co_u32_e32 v21, vcc, 0, v21, vcc
	global_load_dwordx4 v[20:23], v[20:21], off
	s_waitcnt vmcnt(1)
	v_lshlrev_b32_e32 v29, 16, v19
	v_mbcnt_lo_u32_b32 v24, -1, 0
	v_mbcnt_hi_u32_b32 v24, -1, v24
	v_mbcnt_lo_u32_b32 v25, -1, 0
	v_mbcnt_hi_u32_b32 v25, -1, v25
	v_mbcnt_lo_u32_b32 v26, -1, 0
	v_mbcnt_hi_u32_b32 v26, -1, v26
	v_mbcnt_lo_u32_b32 v27, -1, 0
	v_mbcnt_hi_u32_b32 v27, -1, v27
	v_lshlrev_b32_e32 v28, 16, v18
	v_lshlrev_b32_e32 v26, 2, v26
	v_lshlrev_b32_e32 v27, 2, v27
	v_xor_b32_e32 v36, 16, v26
	v_xor_b32_e32 v37, 32, v27
	v_lshlrev_b32_e32 v27, 16, v17
	v_lshlrev_b32_e32 v26, 16, v16
	v_and_b32_e32 v17, 0xffff0000, v17
	v_and_b32_e32 v16, 0xffff0000, v16
	v_and_b32_e32 v19, 0xffff0000, v19
	v_and_b32_e32 v18, 0xffff0000, v18
	v_lshlrev_b32_e32 v24, 2, v24
	v_xor_b32_e32 v34, 4, v24
	v_lshlrev_b32_e32 v25, 2, v25
	v_xor_b32_e32 v35, 8, v25
	s_load_dwordx2 s[4:5], s[18:19], 0xc0
	s_waitcnt lgkmcnt(0)
	s_add_u32 s4, s4, s12
	s_addc_u32 s5, s5, s13
	v_lshl_add_u64 v[24:25], s[4:5], 0, v[0:1]
	s_add_i32 s17, s17, s30
	s_cmpk_gt_i32 s17, 0x3fff
	s_waitcnt vmcnt(0)
	v_lshlrev_b32_e32 v31, 16, v21
	v_lshlrev_b32_e32 v30, 16, v20
	v_and_b32_e32 v21, 0xffff0000, v21
	v_and_b32_e32 v20, 0xffff0000, v20
	v_lshlrev_b32_e32 v33, 16, v23
	v_lshlrev_b32_e32 v32, 16, v22
	v_and_b32_e32 v23, 0xffff0000, v23
	v_and_b32_e32 v22, 0xffff0000, v22
	v_pk_fma_f32 v[26:27], v[4:5], v[30:31], v[26:27] neg_lo:[1,0,0] neg_hi:[1,0,0]
	v_pk_fma_f32 v[16:17], v[4:5], v[20:21], v[16:17] neg_lo:[1,0,0] neg_hi:[1,0,0]
	v_pk_fma_f32 v[20:21], v[4:5], v[32:33], v[28:29] neg_lo:[1,0,0] neg_hi:[1,0,0]
	v_pk_fma_f32 v[18:19], v[4:5], v[22:23], v[18:19] neg_lo:[1,0,0] neg_hi:[1,0,0]
	v_pk_mul_f32 v[22:23], v[26:27], v[26:27]
	v_pk_mul_f32 v[28:29], v[16:17], v[16:17]
	v_mov_b32_e32 v30, v18
	v_add_f32_e32 v22, v22, v28
	v_mov_b32_e32 v31, v20
	v_add_f32_e32 v22, v23, v22
	v_pk_mul_f32 v[30:31], v[30:31], v[30:31]
	v_add_f32_e32 v22, v29, v22
	v_mov_b32_e32 v32, v19
	v_mov_b32_e32 v33, v21
	v_add_f32_e32 v22, v31, v22
	v_pk_mul_f32 v[32:33], v[32:33], v[32:33]
	v_add_f32_e32 v22, v30, v22
	v_add_f32_e32 v22, v33, v22
	v_add_f32_e32 v22, v32, v22
	s_nop 1
	v_mov_b32_dpp v23, v22 quad_perm:[1,0,3,2] row_mask:0xf bank_mask:0xf
	v_add_f32_e32 v22, v22, v23
	s_nop 1
	v_mov_b32_dpp v23, v22 quad_perm:[2,3,0,1] row_mask:0xf bank_mask:0xf
	v_add_f32_e32 v22, v22, v23
	s_nop 1
	v_mov_b32_dpp v23, v22 row_shl:4 row_mask:0xf bank_mask:0x5
	v_mov_b32_dpp v23, v22 row_shr:4 row_mask:0xf bank_mask:0xa
	v_add_f32_e32 v22, v22, v23
	s_nop 1
	v_mov_b32_dpp v23, v22 row_ror:8 row_mask:0xf bank_mask:0xf
	v_add_f32_e32 v22, v22, v23
	v_fmamk_f32 v22, v22, 0x3c000000, v14
	v_mul_f32_e32 v23, 0x4f800000, v22
	v_cmp_gt_f32_e32 vcc, s15, v22
	s_nop 1
	v_cndmask_b32_e32 v22, v22, v23, vcc
	v_sqrt_f32_e32 v23, v22
	s_nop 0
	v_add_u32_e32 v28, -1, v23
	v_add_u32_e32 v29, 1, v23
	v_fma_f32 v30, -v28, v23, v22
	v_fma_f32 v31, -v29, v23, v22
	v_cmp_ge_f32_e64 s[4:5], 0, v30
	s_nop 1
	v_cndmask_b32_e64 v23, v23, v28, s[4:5]
	v_cmp_lt_f32_e64 s[4:5], 0, v31
	s_nop 1
	v_cndmask_b32_e64 v23, v23, v29, s[4:5]
	v_mul_f32_e32 v28, 0x37800000, v23
	v_cndmask_b32_e32 v23, v23, v28, vcc
	v_cmp_class_f32_e32 vcc, v22, v15
	s_nop 1
	v_cndmask_b32_e32 v23, v23, v22, vcc
	v_div_scale_f32 v22, s[4:5], v23, v23, 1.0
	v_rcp_f32_e32 v29, v22
	v_div_scale_f32 v28, vcc, 1.0, v23, 1.0
	v_fma_f32 v30, -v22, v29, 1.0
	v_fmac_f32_e32 v29, v30, v29
	v_mul_f32_e32 v30, v28, v29
	v_fma_f32 v31, -v22, v30, v28
	v_fmac_f32_e32 v30, v31, v29
	v_fma_f32 v22, -v22, v30, v28
	v_div_fmas_f32 v28, v22, v29, v30
	v_add_co_u32_e32 v22, vcc, 0x1e500000, v24
	v_div_fixup_f32 v24, v28, v23, 1.0
	v_pk_mul_f32 v[26:27], v[26:27], v[24:25] op_sel_hi:[1,0]
	v_pk_mul_f32 v[20:21], v[20:21], v[24:25] op_sel_hi:[1,0]
	v_addc_co_u32_e32 v23, vcc, 0, v25, vcc
	v_pk_mul_f32 v[16:17], v[16:17], v[24:25] op_sel_hi:[1,0]
	v_pk_mul_f32 v[18:19], v[18:19], v[24:25] op_sel_hi:[1,0]
	v_pk_mul_f32 v[24:25], v[6:7], v[26:27]
	v_pk_mul_f32 v[20:21], v[10:11], v[20:21]
	v_pk_mul_f32 v[16:17], v[8:9], v[16:17]
	v_pk_mul_f32 v[18:19], v[12:13], v[18:19]
	v_bfe_u32 v30, v24, 16, 1
	v_bfe_u32 v31, v25, 16, 1
	v_bfe_u32 v32, v20, 16, 1
	v_bfe_u32 v33, v21, 16, 1
	v_bfe_u32 v26, v19, 16, 1
	v_bfe_u32 v27, v18, 16, 1
	v_bfe_u32 v28, v17, 16, 1
	v_bfe_u32 v29, v16, 16, 1
	v_add3_u32 v21, v21, v33, s16
	v_add3_u32 v20, v20, v32, s16
	v_add3_u32 v25, v25, v31, s16
	v_add3_u32 v24, v24, v30, s16
	v_add3_u32 v16, v16, v29, s16
	v_add3_u32 v17, v17, v28, s16
	v_add3_u32 v18, v18, v27, s16
	v_add3_u32 v19, v19, v26, s16
	v_lshrrev_b32_e32 v24, 16, v24
	v_lshrrev_b32_e32 v25, 16, v25
	v_lshrrev_b32_e32 v20, 16, v20
	v_lshrrev_b32_e32 v21, 16, v21
	v_and_or_b32 v19, v19, s14, v21
	v_and_or_b32 v18, v18, s14, v20
	v_and_or_b32 v17, v17, s14, v25
	v_and_or_b32 v16, v16, s14, v24
	global_store_dwordx4 v[22:23], v[16:19], off
	s_cbranch_scc0 .LBB0_598

; __device__ __forceinline__ float shx(float v, int o) { const int l = lane_now(); return __int_as_float(__builtin_amdgcn_ds_bpermute((l ^ o) << 2, __float_as_int(v))); }
; __device__ __forceinline__ float wave_sum(float v) {
; #pragma unroll
;     for (int o = 1; o < 64; o <<= 1) v += shx(v, o);
;     return v;
; }
; template <int SRC, int EXTRA, bool OUT8 = false> ...
;     ...
;         float s = 0.f;
; #pragma unroll
;         for (int j = 0; j < 4; ++j) s += (v[j].x + v[j].y) + (v[j].z + v[j].w);
;         const float mean = wave_sum(s) * (1.f / 1024.f); float s2 = 0.f;
; #pragma unroll
;         for (int j = 0; j < 4; ++j) { v[j] = v[j] - mean; s2 += (v[j].x * v[j].x + v[j].y * v[j].y) + (v[j].z * v[j].z + v[j].w * v[j].w); }
;         const float rstd = 1.f / sqrtf(wave_sum(s2) * (1.f / 1024.f) + LN_EPS);
;         if (stats && lane == 0) { stats[2 * row] = mean; stats[2 * row + 1] = rstd; }
.LBB0_840:
	global_load_dwordx4 v[44:47], v[52:53], off offset:-3072
	global_load_dwordx4 v[40:43], v[52:53], off offset:-2048
	global_load_dwordx4 v[36:39], v[52:53], off offset:-1024
	global_load_dwordx4 v[32:35], v[52:53], off
	s_waitcnt vmcnt(3)
	v_mov_b32_e32 v56, v45
	v_mov_b32_e32 v57, v46
	v_mov_b32_e32 v58, v44
	v_mov_b32_e32 v59, v47
	s_waitcnt vmcnt(2)
	v_mov_b32_e32 v60, v41
	v_mov_b32_e32 v61, v42
	v_mov_b32_e32 v62, v40
	v_mov_b32_e32 v63, v43
	v_pk_add_f32 v[56:57], v[56:57], v[58:59]
	v_pk_add_f32 v[58:59], v[60:61], v[62:63]
	v_add_f32_e32 v62, v56, v57
	v_pk_add_f32 v[56:57], v[58:59], v[58:59] op_sel:[0,1] op_sel_hi:[1,0]
	s_waitcnt vmcnt(1)
	v_add_f32_e32 v64, v36, v37
	v_add_f32_e32 v66, v38, v39
	s_waitcnt vmcnt(0)
	v_mov_b32_e32 v69, v32
	v_mov_b32_e32 v65, v34
	v_mov_b32_e32 v67, v35
	v_add_f32_e32 v68, 0, v62
	v_mov_b32_e32 v57, v33
	v_pk_add_f32 v[60:61], v[64:65], v[66:67]
	v_pk_add_f32 v[56:57], v[68:69], v[56:57]
	v_pk_add_f32 v[56:57], v[56:57], v[60:61]
	v_add_f32_e32 v56, v56, v57
	s_nop 1
	v_mov_b32_dpp v48, v56 quad_perm:[1,0,3,2] row_mask:0xf bank_mask:0xf
	v_add_f32_e32 v48, v56, v48
	s_nop 1
	v_mov_b32_dpp v56, v48 quad_perm:[2,3,0,1] row_mask:0xf bank_mask:0xf
	v_add_f32_e32 v48, v48, v56
	s_nop 1
	v_mov_b32_dpp v56, v48 row_shl:4 row_mask:0xf bank_mask:0x5
	v_mov_b32_dpp v56, v48 row_shr:4 row_mask:0xf bank_mask:0xa
	v_add_f32_e32 v48, v48, v56
	s_nop 1
	v_mov_b32_dpp v56, v48 row_ror:8 row_mask:0xf bank_mask:0xf
	v_add_f32_e32 v48, v48, v56
	v_mov_b32_e32 v56, v48
	v_mov_b32_e32 v120, v48
	s_nop 1
	v_permlane16_swap_b32_e32 v56, v120
	v_cndmask_b32_e64 v56, v120, v56, s[98:99]
	v_add_f32_e32 v48, v48, v56
	v_mov_b32_e32 v56, v48
	v_mov_b32_e32 v120, v48
	s_nop 1
	v_permlane32_swap_b32_e32 v56, v120
	v_cndmask_b32_e64 v56, v120, v56, s[100:101]
	v_add_f32_e32 v56, v48, v56
	v_fmamk_f32 v47, v56, 0xba800000, v47
	v_fmamk_f32 v45, v56, 0xba800000, v45
	v_fmamk_f32 v43, v56, 0xba800000, v43
	v_fmamk_f32 v41, v56, 0xba800000, v41
	v_fmamk_f32 v46, v56, 0xba800000, v46
	v_fmac_f32_e32 v44, 0xba800000, v56
	v_fmamk_f32 v42, v56, 0xba800000, v42
	v_fmac_f32_e32 v40, 0xba800000, v56
	v_fmamk_f32 v39, v56, 0xba800000, v39
	v_fmamk_f32 v37, v56, 0xba800000, v37
	v_mul_f32_e32 v48, v45, v45
	v_mul_f32_e32 v58, v47, v47
	v_mul_f32_e32 v59, v41, v41
	v_mul_f32_e32 v60, v43, v43
	v_fmamk_f32 v38, v56, 0xba800000, v38
	v_fmac_f32_e32 v36, 0xba800000, v56
	v_fmamk_f32 v35, v56, 0xba800000, v35
	v_fmamk_f32 v33, v56, 0xba800000, v33
	v_mul_f32_e32 v61, v37, v37
	v_mul_f32_e32 v62, v39, v39
	v_fmac_f32_e32 v48, v44, v44
	v_fmac_f32_e32 v58, v46, v46
	v_fmac_f32_e32 v59, v40, v40
	v_fmac_f32_e32 v60, v42, v42
	v_fmamk_f32 v34, v56, 0xba800000, v34
	v_fmac_f32_e32 v32, 0xba800000, v56
	v_mul_f32_e32 v63, v33, v33
	v_mul_f32_e32 v64, v35, v35
	v_fmac_f32_e32 v61, v36, v36
	v_fmac_f32_e32 v62, v38, v38
	v_add_f32_e32 v48, v48, v58
	v_add_f32_e32 v58, v59, v60
	v_fmac_f32_e32 v63, v32, v32
	v_fmac_f32_e32 v64, v34, v34
	v_add_f32_e32 v59, v61, v62
	v_add_f32_e32 v48, v48, v58
	v_add_f32_e32 v60, v63, v64
	v_add_f32_e32 v48, v59, v48
	v_add_f32_e32 v48, v60, v48
	s_nop 1
	v_mov_b32_dpp v57, v48 quad_perm:[1,0,3,2] row_mask:0xf bank_mask:0xf
	v_add_f32_e32 v48, v48, v57
	s_nop 1
	v_mov_b32_dpp v57, v48 quad_perm:[2,3,0,1] row_mask:0xf bank_mask:0xf
	v_add_f32_e32 v48, v48, v57
	s_nop 1
	v_mov_b32_dpp v57, v48 row_shl:4 row_mask:0xf bank_mask:0x5
	v_mov_b32_dpp v57, v48 row_shr:4 row_mask:0xf bank_mask:0xa
	v_add_f32_e32 v48, v48, v57
	s_nop 1
	v_mov_b32_dpp v57, v48 row_ror:8 row_mask:0xf bank_mask:0xf
	v_add_f32_e32 v48, v48, v57
	v_mov_b32_e32 v57, v48
	v_mov_b32_e32 v120, v48
	s_nop 1
	v_permlane16_swap_b32_e32 v57, v120
	v_cndmask_b32_e64 v57, v120, v57, s[98:99]
	v_add_f32_e32 v48, v48, v57
	v_mov_b32_e32 v57, v48
	v_mov_b32_e32 v120, v48
	s_nop 1
	v_permlane32_swap_b32_e32 v57, v120
	v_cndmask_b32_e64 v57, v120, v57, s[100:101]
	v_add_f32_e32 v48, v48, v57
	v_fmamk_f32 v48, v48, 0x3a800000, v54
	v_mul_f32_e32 v57, 0x4f800000, v48
	v_cmp_gt_f32_e32 vcc, s22, v48
	s_nop 1
	v_cndmask_b32_e32 v48, v48, v57, vcc
	v_sqrt_f32_e32 v57, v48
	s_nop 0
	v_add_u32_e32 v58, -1, v57
	v_add_u32_e32 v59, 1, v57
	v_fma_f32 v60, -v58, v57, v48
	v_fma_f32 v61, -v59, v57, v48
	v_cmp_ge_f32_e64 s[12:13], 0, v60
	s_nop 1
	v_cndmask_b32_e64 v57, v57, v58, s[12:13]
	v_cmp_lt_f32_e64 s[12:13], 0, v61
	s_nop 1
	v_cndmask_b32_e64 v57, v57, v59, s[12:13]
	v_mul_f32_e32 v58, 0x37800000, v57
	v_cndmask_b32_e32 v57, v57, v58, vcc
	v_cmp_class_f32_e32 vcc, v48, v55
	s_nop 1
	v_cndmask_b32_e32 v48, v57, v48, vcc
	v_div_scale_f32 v57, s[12:13], v48, v48, 1.0
	v_rcp_f32_e32 v58, v57
	v_div_scale_f32 v59, vcc, 1.0, v48, 1.0
	v_fma_f32 v60, -v57, v58, 1.0
	v_fmac_f32_e32 v58, v60, v58
	v_mul_f32_e32 v60, v59, v58
	v_fma_f32 v61, -v57, v60, v59
	v_fmac_f32_e32 v60, v61, v58
	v_fma_f32 v57, -v57, v60, v59
	v_div_fmas_f32 v57, v57, v58, v60
	v_div_fixup_f32 v48, v57, v48, 1.0
	s_and_saveexec_b64 s[12:13], s[10:11]
	s_cbranch_execz .LBB0_839
	s_ashr_i32 s15, s14, 31
	s_lshl_b64 s[24:25], s[14:15], 2
	s_add_u32 s24, s3, s24
	v_mul_f32_e32 v56, 0x3a800000, v56
	s_addc_u32 s25, s20, s25
	v_mov_b32_e32 v57, v48
	global_store_dwordx2 v49, v[56:57], s[24:25]
	s_branch .LBB0_839

; __device__ __forceinline__ float shx(float v, int o) { const int l = lane_now(); return __int_as_float(__builtin_amdgcn_ds_bpermute((l ^ o) << 2, __float_as_int(v))); }
;     __device__ __forceinline__ void operator()(const f32x4 (&acc)[2][2][4][2], const Unit& u, int wr, int wc, int fr, int fq) const {
;     ...
;                     for (int bj = 0; bj < 2; ++bj) { const f32x4 v0 = acc[ai][bj][m][0] * sc, v1 = acc[ai][bj][m][1] * sc;
;                         float ss = (v0[0] * v0[0] + v0[1] * v0[1]) + (v0[2] * v0[2] + v0[3] * v0[3]) + (v1[0] * v1[0] + v1[1] * v1[1]) + (v1[2] * v1[2] + v1[3] * v1[3]);
;                         ss += shx(ss, 16); ss += shx(ss, 32); mx[bj] = fmaxf(mx[bj], ss); }
; #pragma unroll
;             for (int bj = 0; bj < 2; ++bj) { float v = mx[bj]; v = fmaxf(v, shx(v, 1)); v = fmaxf(v, shx(v, 2)); v = fmaxf(v, shx(v, 4)); v = fmaxf(v, shx(v, 8));
;                 if (fr == 0 && fq == 0) atomicMax(nrm + (pn >> 1) * 16 + (4 * (pn & 1) + 2 * bj + (wc >> 1)) * 2 + (wc & 1), __float_as_uint(v)); }
.LBB0_1336:
	v_mov_b32_e32 v139, v138
	v_pk_mul_f32 v[0:1], v[138:139], v[126:127]
	v_pk_mul_f32 v[4:5], v[138:139], v[122:123]
	v_mul_f32_e32 v122, v143, v143
	v_mul_f32_e32 v1, v1, v1
	v_fmac_f32_e32 v122, v142, v142
	v_fmac_f32_e32 v1, v0, v0
	v_add_f32_e32 v0, v122, v1
	v_mul_f32_e32 v1, v141, v141
	v_fmac_f32_e32 v1, v140, v140
	v_add_f32_e32 v0, v0, v1
	v_mul_f32_e32 v1, v5, v5
	v_fmac_f32_e32 v1, v4, v4
	v_add_f32_e32 v0, v1, v0
	v_pk_mul_f32 v[4:5], v[138:139], v[110:111]
	v_mov_b32_e32 v1, v0
	v_mov_b32_e32 v200, v0
	s_nop 1
	v_permlane16_swap_b32_e32 v1, v200
	v_cndmask_b32_e64 v1, v200, v1, s[98:99]
	v_mul_f32_e32 v110, v125, v125
	v_fmac_f32_e32 v110, v124, v124
	v_mul_f32_e32 v111, v5, v5
	v_fmac_f32_e32 v111, v4, v4
	v_add_f32_e32 v0, v0, v1
	v_pk_mul_f32 v[4:5], v[138:139], v[106:107]
	v_mov_b32_e32 v1, v0
	v_mov_b32_e32 v200, v0
	s_nop 1
	v_permlane32_swap_b32_e32 v1, v200
	v_cndmask_b32_e64 v1, v200, v1, s[100:101]
	v_mul_f32_e32 v106, v117, v117
	v_fmac_f32_e32 v106, v116, v116
	v_pk_mul_f32 v[90:91], v[138:139], v[90:91]
	v_pk_mul_f32 v[94:95], v[138:139], v[94:95]
	v_add_f32_e32 v122, v0, v1
	v_pk_mul_f32 v[0:1], v[138:139], v[118:119]
	v_mbcnt_lo_u32_b32 v118, -1, 0
	v_mbcnt_hi_u32_b32 v118, -1, v118
	v_mbcnt_lo_u32_b32 v119, -1, 0
	v_mbcnt_hi_u32_b32 v119, -1, v119
	v_mul_f32_e32 v95, v95, v95
	v_mul_f32_e32 v1, v1, v1
	v_fmac_f32_e32 v1, v0, v0
	v_add_f32_e32 v0, v110, v1
	v_mul_f32_e32 v1, v121, v121
	v_fmac_f32_e32 v1, v120, v120
	v_add_f32_e32 v110, v0, v1
	v_pk_mul_f32 v[0:1], v[138:139], v[114:115]
	v_fmac_f32_e32 v95, v94, v94
	v_mul_f32_e32 v1, v1, v1
	v_fmac_f32_e32 v1, v0, v0
	v_add_f32_e32 v0, v106, v1
	v_mul_f32_e32 v1, v109, v109
	v_fmac_f32_e32 v1, v108, v108
	v_add_f32_e32 v0, v0, v1
	v_mul_f32_e32 v1, v5, v5
	v_fmac_f32_e32 v1, v4, v4
	v_add_f32_e32 v0, v1, v0
	v_mov_b32_e32 v1, v0
	v_mov_b32_e32 v200, v0
	s_nop 1
	v_permlane16_swap_b32_e32 v1, v200
	v_cndmask_b32_e64 v1, v200, v1, s[98:99]
	v_add_f32_e32 v4, v111, v110
	v_mov_b32_e32 v5, v4
	v_mov_b32_e32 v200, v4
	s_nop 1
	v_permlane16_swap_b32_e32 v5, v200
	v_cndmask_b32_e64 v5, v200, v5, s[98:99]
	v_pk_mul_f32 v[86:87], v[138:139], v[86:87]
	v_add_f32_e32 v106, v0, v1
	v_mbcnt_lo_u32_b32 v94, -1, 0
	v_mbcnt_hi_u32_b32 v94, -1, v94
	v_mul_f32_e32 v87, v87, v87
	v_mov_b32_e32 v107, v106
	v_mov_b32_e32 v200, v106
	s_nop 1
	v_permlane32_swap_b32_e32 v107, v200
	v_cndmask_b32_e64 v107, v200, v107, s[100:101]
	v_add_f32_e32 v0, v4, v5
	v_fmac_f32_e32 v87, v86, v86
	v_pk_mul_f32 v[78:79], v[138:139], v[78:79]
	v_pk_mul_f32 v[74:75], v[138:139], v[74:75]
	v_add_f32_e32 v4, v106, v107
	v_max3_f32 v106, v122, 0, v4
	v_pk_mul_f32 v[4:5], v[138:139], v[102:103]
	v_mul_f32_e32 v102, v113, v113
	v_mul_f32_e32 v5, v5, v5
	v_fmac_f32_e32 v102, v112, v112
	v_fmac_f32_e32 v5, v4, v4
	v_add_f32_e32 v4, v102, v5
	v_mul_f32_e32 v5, v105, v105
	v_fmac_f32_e32 v5, v104, v104
	v_add_f32_e32 v102, v4, v5
	v_pk_mul_f32 v[4:5], v[138:139], v[98:99]
	v_mul_f32_e32 v98, v101, v101
	v_mul_f32_e32 v5, v5, v5
	v_fmac_f32_e32 v98, v100, v100
	v_fmac_f32_e32 v5, v4, v4
	v_add_f32_e32 v4, v98, v5
	v_mul_f32_e32 v5, v93, v93
	v_fmac_f32_e32 v5, v92, v92
	v_add_f32_e32 v4, v4, v5
	v_mul_f32_e32 v5, v91, v91
	v_fmac_f32_e32 v5, v90, v90
	v_mbcnt_lo_u32_b32 v103, -1, 0
	v_mbcnt_hi_u32_b32 v103, -1, v103
	v_add_f32_e32 v4, v5, v4
	v_mov_b32_e32 v5, v4
	v_mov_b32_e32 v200, v4
	s_nop 1
	v_permlane16_swap_b32_e32 v5, v200
	v_cndmask_b32_e64 v5, v200, v5, s[98:99]
	v_add_f32_e32 v90, v95, v102
	v_mov_b32_e32 v91, v90
	v_mov_b32_e32 v200, v90
	s_nop 1
	v_permlane16_swap_b32_e32 v91, v200
	v_cndmask_b32_e64 v91, v200, v91, s[98:99]
	v_mul_f32_e32 v77, v77, v77
	v_add_f32_e32 v92, v4, v5
	v_fmac_f32_e32 v77, v76, v76
	v_mov_b32_e32 v93, v92
	v_mov_b32_e32 v200, v92
	s_nop 1
	v_permlane32_swap_b32_e32 v93, v200
	v_cndmask_b32_e64 v93, v200, v93, s[100:101]
	v_add_f32_e32 v4, v90, v91
	v_mul_f32_e32 v91, v97, v97
	v_fmac_f32_e32 v91, v96, v96
	v_add_f32_e32 v86, v91, v87
	v_mul_f32_e32 v87, v89, v89
	v_fmac_f32_e32 v87, v88, v88
	v_add_f32_e32 v86, v86, v87
	v_mul_f32_e32 v87, v79, v79
	v_fmac_f32_e32 v87, v78, v78
	v_pk_mul_f32 v[78:79], v[138:139], v[82:83]
	v_mul_f32_e32 v82, v85, v85
	v_mul_f32_e32 v79, v79, v79
	v_fmac_f32_e32 v82, v84, v84
	v_fmac_f32_e32 v79, v78, v78
	v_add_f32_e32 v78, v82, v79
	v_mul_f32_e32 v75, v75, v75
	v_add_f32_e32 v76, v78, v77
	v_fmac_f32_e32 v75, v74, v74
	v_mbcnt_lo_u32_b32 v88, -1, 0
	v_mbcnt_hi_u32_b32 v88, -1, v88
	v_mbcnt_lo_u32_b32 v89, -1, 0
	v_mbcnt_hi_u32_b32 v89, -1, v89
	v_add_f32_e32 v74, v75, v76
	v_mov_b32_e32 v75, v74
	v_mov_b32_e32 v200, v74
	s_nop 1
	v_permlane16_swap_b32_e32 v75, v200
	v_cndmask_b32_e64 v75, v200, v75, s[98:99]
	v_add_f32_e32 v76, v87, v86
	v_mov_b32_e32 v77, v76
	v_mov_b32_e32 v200, v76
	s_nop 1
	v_permlane16_swap_b32_e32 v77, v200
	v_cndmask_b32_e64 v77, v200, v77, s[98:99]
	v_pk_mul_f32 v[62:63], v[138:139], v[62:63]
	v_add_f32_e32 v78, v74, v75
	v_pk_mul_f32 v[70:71], v[138:139], v[70:71]
	v_mul_f32_e32 v69, v69, v69
	v_mul_f32_e32 v63, v63, v63
	v_mov_b32_e32 v79, v78
	v_mov_b32_e32 v200, v78
	s_nop 1
	v_permlane32_swap_b32_e32 v79, v200
	v_cndmask_b32_e64 v79, v200, v79, s[100:101]
	v_add_f32_e32 v74, v76, v77
	v_mul_f32_e32 v77, v81, v81
	v_mul_f32_e32 v71, v71, v71
	v_fmac_f32_e32 v69, v68, v68
	v_fmac_f32_e32 v63, v62, v62
	v_fmac_f32_e32 v77, v80, v80
	v_fmac_f32_e32 v71, v70, v70
	v_pk_mul_f32 v[58:59], v[138:139], v[58:59]
	v_add_f32_e32 v62, v69, v63
	v_mul_f32_e32 v63, v65, v65
	v_pk_mul_f32 v[54:55], v[138:139], v[54:55]
	v_pk_mul_f32 v[66:67], v[138:139], v[66:67]
	v_add_f32_e32 v70, v77, v71
; __device__ __forceinline__ float shx(float v, int o) { const int l = lane_now(); return __int_as_float(__builtin_amdgcn_ds_bpermute((l ^ o) << 2, __float_as_int(v))); }
;     __device__ __forceinline__ void operator()(const f32x4 (&acc)[2][2][4][2], const Unit& u, int wr, int wc, int fr, int fq) const {
;     ...
;                     for (int bj = 0; bj < 2; ++bj) { const f32x4 v0 = acc[ai][bj][m][0] * sc, v1 = acc[ai][bj][m][1] * sc;
;                         float ss = (v0[0] * v0[0] + v0[1] * v0[1]) + (v0[2] * v0[2] + v0[3] * v0[3]) + (v1[0] * v1[0] + v1[1] * v1[1]) + (v1[2] * v1[2] + v1[3] * v1[3]);
;                         ss += shx(ss, 16); ss += shx(ss, 32); mx[bj] = fmaxf(mx[bj], ss); }
	v_mul_f32_e32 v71, v73, v73
	v_fmac_f32_e32 v63, v64, v64
	v_mul_f32_e32 v59, v59, v59
	v_mul_f32_e32 v61, v61, v61
	v_mul_f32_e32 v55, v55, v55
	v_fmac_f32_e32 v71, v72, v72
	v_mul_f32_e32 v67, v67, v67
	v_add_f32_e32 v62, v62, v63
	v_fmac_f32_e32 v59, v58, v58
	v_fmac_f32_e32 v61, v60, v60
	v_fmac_f32_e32 v55, v54, v54
	v_add_f32_e32 v70, v70, v71
	v_fmac_f32_e32 v67, v66, v66
	v_mbcnt_lo_u32_b32 v66, -1, 0
	v_mbcnt_hi_u32_b32 v66, -1, v66
	v_mbcnt_lo_u32_b32 v71, -1, 0
	v_mbcnt_hi_u32_b32 v71, -1, v71
	v_add_f32_e32 v58, v59, v62
	v_add_f32_e32 v54, v61, v55
	v_mul_f32_e32 v55, v57, v57
	v_pk_mul_f32 v[46:47], v[138:139], v[46:47]
	v_fmac_f32_e32 v55, v56, v56
	v_add_f32_e32 v54, v54, v55
	v_mul_f32_e32 v55, v47, v47
	v_mov_b32_e32 v59, v58
	v_mov_b32_e32 v200, v58
	s_nop 1
	v_permlane16_swap_b32_e32 v59, v200
	v_cndmask_b32_e64 v59, v200, v59, s[98:99]
	v_fmac_f32_e32 v55, v46, v46
	v_pk_mul_f32 v[46:47], v[138:139], v[50:51]
	v_mul_f32_e32 v50, v53, v53
	v_mul_f32_e32 v47, v47, v47
	v_pk_mul_f32 v[42:43], v[138:139], v[42:43]
	v_fmac_f32_e32 v50, v52, v52
	v_fmac_f32_e32 v47, v46, v46
	v_mul_f32_e32 v45, v45, v45
	v_add_f32_e32 v46, v50, v47
	v_fmac_f32_e32 v45, v44, v44
	v_mul_f32_e32 v43, v43, v43
	v_add_f32_e32 v44, v46, v45
	v_fmac_f32_e32 v43, v42, v42
	v_add_f32_e32 v64, v58, v59
	v_mbcnt_lo_u32_b32 v56, -1, 0
	v_mbcnt_hi_u32_b32 v56, -1, v56
	v_mbcnt_lo_u32_b32 v57, -1, 0
	v_mbcnt_hi_u32_b32 v57, -1, v57
	v_add_f32_e32 v42, v43, v44
	v_mov_b32_e32 v43, v42
	v_mov_b32_e32 v200, v42
	s_nop 1
	v_permlane16_swap_b32_e32 v43, v200
	v_cndmask_b32_e64 v43, v200, v43, s[98:99]
	v_add_f32_e32 v44, v55, v54
	v_mov_b32_e32 v45, v44
	v_mov_b32_e32 v200, v44
	s_nop 1
	v_permlane16_swap_b32_e32 v45, v200
	v_cndmask_b32_e64 v45, v200, v45, s[98:99]
	v_pk_mul_f32 v[38:39], v[138:139], v[38:39]
	v_add_f32_e32 v46, v42, v43
	v_mul_f32_e32 v39, v39, v39
	v_mov_b32_e32 v47, v46
	v_mov_b32_e32 v200, v46
	s_nop 1
	v_permlane32_swap_b32_e32 v47, v200
	v_cndmask_b32_e64 v47, v200, v47, s[100:101]
	v_add_f32_e32 v42, v44, v45
	v_mul_f32_e32 v45, v49, v49
	v_pk_mul_f32 v[30:31], v[138:139], v[30:31]
	v_fmac_f32_e32 v45, v48, v48
	v_fmac_f32_e32 v39, v38, v38
	v_add_f32_e32 v38, v45, v39
	v_mul_f32_e32 v39, v41, v41
	v_mul_f32_e32 v31, v31, v31
	v_fmac_f32_e32 v39, v40, v40
	v_fmac_f32_e32 v31, v30, v30
	v_add_f32_e32 v38, v38, v39
	v_add_f32_e32 v38, v31, v38
	v_mov_b32_e32 v39, v38
	v_mov_b32_e32 v200, v38
	s_nop 1
	v_permlane16_swap_b32_e32 v39, v200
	v_cndmask_b32_e64 v39, v200, v39, s[98:99]
	v_pk_mul_f32 v[30:31], v[138:139], v[34:35]
	v_mul_f32_e32 v34, v37, v37
	v_mul_f32_e32 v31, v31, v31
	v_fmac_f32_e32 v34, v36, v36
	v_fmac_f32_e32 v31, v30, v30
	v_mul_f32_e32 v29, v29, v29
	v_add_f32_e32 v30, v34, v31
	v_fmac_f32_e32 v29, v28, v28
	v_pk_mul_f32 v[22:23], v[138:139], v[22:23]
	v_pk_mul_f32 v[26:27], v[138:139], v[26:27]
	v_add_f32_e32 v28, v30, v29
	v_mul_f32_e32 v30, v33, v33
	v_mul_f32_e32 v23, v23, v23
	v_mul_f32_e32 v27, v27, v27
	v_fmac_f32_e32 v30, v32, v32
	v_fmac_f32_e32 v23, v22, v22
	v_mbcnt_lo_u32_b32 v40, -1, 0
	v_mbcnt_hi_u32_b32 v40, -1, v40
	v_fmac_f32_e32 v27, v26, v26
	v_add_f32_e32 v22, v30, v23
	v_mul_f32_e32 v23, v25, v25
	v_pk_mul_f32 v[14:15], v[138:139], v[14:15]
	v_fmac_f32_e32 v23, v24, v24
	v_add_f32_e32 v28, v27, v28
	v_add_f32_e32 v22, v22, v23
	v_mul_f32_e32 v23, v15, v15
	v_mov_b32_e32 v29, v28
	v_mov_b32_e32 v200, v28
	s_nop 1
	v_permlane16_swap_b32_e32 v29, v200
	v_cndmask_b32_e64 v29, v200, v29, s[98:99]
	v_fmac_f32_e32 v23, v14, v14
	v_pk_mul_f32 v[14:15], v[138:139], v[18:19]
	v_mul_f32_e32 v18, v21, v21
	v_mul_f32_e32 v15, v15, v15
	v_pk_mul_f32 v[10:11], v[138:139], v[10:11]
	v_fmac_f32_e32 v18, v20, v20
	v_fmac_f32_e32 v15, v14, v14
	v_mul_f32_e32 v13, v13, v13
	v_add_f32_e32 v14, v18, v15
	v_fmac_f32_e32 v13, v12, v12
	v_mul_f32_e32 v11, v11, v11
	v_add_f32_e32 v12, v14, v13
	v_fmac_f32_e32 v11, v10, v10
	v_add_f32_e32 v28, v28, v29
	v_mbcnt_lo_u32_b32 v24, -1, 0
; __device__ __forceinline__ float shx(float v, int o) { const int l = lane_now(); return __int_as_float(__builtin_amdgcn_ds_bpermute((l ^ o) << 2, __float_as_int(v))); }
;     __device__ __forceinline__ void operator()(const f32x4 (&acc)[2][2][4][2], const Unit& u, int wr, int wc, int fr, int fq) const {
;     ...
;                     for (int bj = 0; bj < 2; ++bj) { const f32x4 v0 = acc[ai][bj][m][0] * sc, v1 = acc[ai][bj][m][1] * sc;
;                         float ss = (v0[0] * v0[0] + v0[1] * v0[1]) + (v0[2] * v0[2] + v0[3] * v0[3]) + (v1[0] * v1[0] + v1[1] * v1[1]) + (v1[2] * v1[2] + v1[3] * v1[3]);
;                         ss += shx(ss, 16); ss += shx(ss, 32); mx[bj] = fmaxf(mx[bj], ss); }
; #pragma unroll
;             for (int bj = 0; bj < 2; ++bj) { float v = mx[bj]; v = fmaxf(v, shx(v, 1)); v = fmaxf(v, shx(v, 2)); v = fmaxf(v, shx(v, 4)); v = fmaxf(v, shx(v, 8));
;                 if (fr == 0 && fq == 0) atomicMax(nrm + (pn >> 1) * 16 + (4 * (pn & 1) + 2 * bj + (wc >> 1)) * 2 + (wc & 1), __float_as_uint(v)); }
	v_mbcnt_hi_u32_b32 v24, -1, v24
	v_mbcnt_lo_u32_b32 v25, -1, 0
	v_mbcnt_hi_u32_b32 v25, -1, v25
	v_add_f32_e32 v10, v11, v12
	v_mov_b32_e32 v11, v10
	v_mov_b32_e32 v200, v10
	s_nop 1
	v_permlane16_swap_b32_e32 v11, v200
	v_cndmask_b32_e64 v11, v200, v11, s[98:99]
	v_add_f32_e32 v12, v23, v22
	v_mov_b32_e32 v13, v12
	v_mov_b32_e32 v200, v12
	s_nop 1
	v_permlane16_swap_b32_e32 v13, v200
	v_cndmask_b32_e64 v13, v200, v13, s[98:99]
	v_add_f32_e32 v11, v10, v11
	v_add_f32_e32 v62, v67, v70
	v_mov_b32_e32 v63, v62
	v_mov_b32_e32 v200, v62
	s_nop 1
	v_permlane16_swap_b32_e32 v63, v200
	v_cndmask_b32_e64 v63, v200, v63, s[98:99]
	v_mov_b32_e32 v65, v64
	v_mov_b32_e32 v200, v64
	s_nop 1
	v_permlane32_swap_b32_e32 v65, v200
	v_cndmask_b32_e64 v65, v200, v65, s[100:101]
	v_pk_mul_f32 v[6:7], v[138:139], v[6:7]
	v_mov_b32_e32 v29, v28
	v_mov_b32_e32 v200, v28
	s_nop 1
	v_permlane32_swap_b32_e32 v29, v200
	v_cndmask_b32_e64 v29, v200, v29, s[100:101]
	v_mov_b32_e32 v14, v11
	v_mov_b32_e32 v200, v11
	s_nop 1
	v_permlane32_swap_b32_e32 v14, v200
	v_cndmask_b32_e64 v14, v200, v14, s[100:101]
	v_add_f32_e32 v10, v12, v13
	v_mul_f32_e32 v13, v17, v17
	v_mul_f32_e32 v7, v7, v7
	v_fmac_f32_e32 v13, v16, v16
	v_fmac_f32_e32 v7, v6, v6
	v_pk_mul_f32 v[2:3], v[138:139], v[2:3]
	v_add_f32_e32 v6, v13, v7
	v_mul_f32_e32 v7, v9, v9
	v_add_f32_e32 v90, v92, v93
	v_add_f32_e32 v76, v78, v79
	v_fmac_f32_e32 v7, v8, v8
	v_mul_f32_e32 v3, v3, v3
	v_max3_f32 v76, v106, v90, v76
	v_add_f32_e32 v58, v62, v63
	v_add_f32_e32 v62, v64, v65
	v_add_f32_e32 v44, v46, v47
	v_add_f32_e32 v6, v6, v7
	v_fmac_f32_e32 v3, v2, v2
	v_max3_f32 v44, v76, v62, v44
	v_add_f32_e32 v15, v28, v29
	v_add_f32_e32 v11, v11, v14
	v_max3_f32 v11, v44, v15, v11
	s_nop 1
	v_mov_b32_dpp v8, v11 quad_perm:[1,0,3,2] row_mask:0xf bank_mask:0xf
	v_add_f32_e32 v3, v3, v6
	v_mov_b32_e32 v6, v3
	v_mov_b32_e32 v200, v3
	s_nop 1
	v_permlane16_swap_b32_e32 v6, v200
	v_cndmask_b32_e64 v6, v200, v6, s[98:99]
	v_max_f32_e32 v2, v8, v8
	v_max_f32_e32 v8, v11, v2
	s_nop 1
	v_mov_b32_dpp v9, v8 quad_perm:[2,3,0,1] row_mask:0xf bank_mask:0xf
	v_add_f32_e32 v3, v3, v6
	v_max_f32_e32 v7, v9, v9
	v_max_f32_e32 v7, v8, v7
	s_nop 1
	v_mov_b32_dpp v8, v7 row_shl:4 row_mask:0xf bank_mask:0x5
	v_mov_b32_dpp v8, v7 row_shr:4 row_mask:0xf bank_mask:0xa
	v_lshlrev_b32_e32 v12, 2, v25
	v_max_f32_e32 v8, v8, v8
	v_max_f32_e32 v7, v7, v8
	v_add_f32_e32 v26, v38, v39
	v_xor_b32_e32 v12, 0x80, v12
	v_mov_b32_e32 v1, v0
	v_mov_b32_e32 v200, v0
	s_nop 1
	v_permlane32_swap_b32_e32 v1, v200
	v_cndmask_b32_e64 v1, v200, v1, s[100:101]
	v_mov_b32_e32 v5, v4
	v_mov_b32_e32 v200, v4
	s_nop 1
	v_permlane32_swap_b32_e32 v5, v200
	v_cndmask_b32_e64 v5, v200, v5, s[100:101]
	v_mov_b32_e32 v75, v74
	v_mov_b32_e32 v200, v74
	s_nop 1
	v_permlane32_swap_b32_e32 v75, v200
	v_cndmask_b32_e64 v75, v200, v75, s[100:101]
	v_mov_b32_e32 v59, v58
	v_mov_b32_e32 v200, v58
	s_nop 1
	v_permlane32_swap_b32_e32 v59, v200
	v_cndmask_b32_e64 v59, v200, v59, s[100:101]
	v_mov_b32_e32 v43, v42
	v_mov_b32_e32 v200, v42
	s_nop 1
	v_permlane32_swap_b32_e32 v43, v200
	v_cndmask_b32_e64 v43, v200, v43, s[100:101]
	v_mov_b32_e32 v27, v26
	v_mov_b32_e32 v200, v26
	s_nop 1
	v_permlane32_swap_b32_e32 v27, v200
	v_cndmask_b32_e64 v27, v200, v27, s[100:101]
	v_mov_b32_e32 v2, v10
	v_mov_b32_e32 v200, v10
	s_nop 1
	v_permlane32_swap_b32_e32 v2, v200
	v_cndmask_b32_e64 v2, v200, v2, s[100:101]
	v_mov_b32_e32 v6, v3
	v_mov_b32_e32 v200, v3
	s_nop 1
	v_permlane32_swap_b32_e32 v6, v200
	v_cndmask_b32_e64 v6, v200, v6, s[100:101]
	s_nop 1
	v_mov_b32_dpp v8, v7 row_ror:8 row_mask:0xf bank_mask:0xf
	s_lshl_b32 s10, s63, 3
	v_or_b32_e32 v9, v163, v162
	s_lshl_b32 s12, s22, 4
	s_and_b32 s10, s10, 8
	v_cmp_eq_u32_e32 vcc, 0, v9
	s_ashr_i32 s13, s12, 31
	s_or_b32 s26, s10, s83
	s_and_saveexec_b64 s[22:23], vcc
	s_cbranch_execz .LBB0_1341
	v_max_f32_e32 v8, v8, v8
	v_max_f32_e32 v7, v7, v7
	s_mov_b64 s[10:11], exec
	v_max_f32_e32 v7, v7, v8
	s_mov_b32 s42, 0

; __device__ __forceinline__ float shx(float v, int o) { const int l = lane_now(); return __int_as_float(__builtin_amdgcn_ds_bpermute((l ^ o) << 2, __float_as_int(v))); }
;     __device__ __forceinline__ void operator()(const f32x4 (&acc)[2][2][4][2], const Unit& u, int wr, int wc, int fr, int fq) const {
;     ...
;                         ss += shx(ss, 16); ss += shx(ss, 32); mx[bj] = fmaxf(mx[bj], ss); }
; #pragma unroll
;             for (int bj = 0; bj < 2; ++bj) { float v = mx[bj]; v = fmaxf(v, shx(v, 1)); v = fmaxf(v, shx(v, 2)); v = fmaxf(v, shx(v, 4)); v = fmaxf(v, shx(v, 8));
;                 if (fr == 0 && fq == 0) atomicMax(nrm + (pn >> 1) * 16 + (4 * (pn & 1) + 2 * bj + (wc >> 1)) * 2 + (wc & 1), __float_as_uint(v)); }
.LBB0_1341:
	s_or_b64 exec, exec, s[22:23]
	s_waitcnt lgkmcnt(8)
	v_add_f32_e32 v0, v0, v1
	s_waitcnt lgkmcnt(7)
	v_add_f32_e32 v1, v4, v5
	v_max3_f32 v0, v0, 0, v1
	s_waitcnt lgkmcnt(6)
	v_add_f32_e32 v1, v74, v75
	s_waitcnt lgkmcnt(5)
	v_add_f32_e32 v4, v58, v59
	v_max3_f32 v0, v0, v1, v4
	s_waitcnt lgkmcnt(4)
	v_add_f32_e32 v1, v42, v43
	s_waitcnt lgkmcnt(3)
	v_add_f32_e32 v4, v26, v27
	v_max3_f32 v0, v0, v1, v4
	s_waitcnt lgkmcnt(2)
	v_add_f32_e32 v1, v10, v2
	s_waitcnt lgkmcnt(1)
	v_add_f32_e32 v2, v3, v6
	v_max3_f32 v0, v0, v1, v2
	s_nop 0
	s_nop 1
	v_mov_b32_dpp v1, v0 quad_perm:[1,0,3,2] row_mask:0xf bank_mask:0xf
	v_max_f32_e32 v1, v1, v1
	v_max_f32_e32 v0, v0, v1
	s_nop 0
	s_nop 1
	v_mov_b32_dpp v1, v0 quad_perm:[2,3,0,1] row_mask:0xf bank_mask:0xf
	v_max_f32_e32 v1, v1, v1
	v_max_f32_e32 v0, v0, v1
	s_nop 0
	s_nop 1
	v_mov_b32_dpp v1, v0 row_shl:4 row_mask:0xf bank_mask:0x5
	v_mov_b32_dpp v1, v0 row_shr:4 row_mask:0xf bank_mask:0xa
	v_max_f32_e32 v1, v1, v1
	v_max_f32_e32 v0, v0, v1
	s_nop 0
	s_nop 1
	v_mov_b32_dpp v1, v0 row_ror:8 row_mask:0xf bank_mask:0xf
	s_and_saveexec_b64 s[10:11], vcc
	s_cbranch_execz .LBB0_1346
	v_max_f32_e32 v1, v1, v1
	v_max_f32_e32 v0, v0, v0
	s_mov_b64 s[22:23], exec
	v_max_f32_e32 v0, v0, v1
	s_mov_b32 s42, 0

; __device__ __forceinline__ float shx(float v, int o) { const int l = lane_now(); return __int_as_float(__builtin_amdgcn_ds_bpermute((l ^ o) << 2, __float_as_int(v))); }
; #define in KArgIn()
; #define FRESH_IDS() const int tid = tid_fresh(wv), lane = tid & 63, wave = wv
; __device__ __forceinline__ float wave_sum(float v) {
; #pragma unroll
;     for (int o = 1; o < 64; o <<= 1) v += shx(v, o);
;     return v;
; }
; template <int l, int SEL> __device__ __forceinline__ void layer_body(const Args& args, LAS unsigned char* ldsp, unsigned char* lds, const int G, const int bx, const int vcu, const int wv) {
;     ...
;             FRESH_IDS();
;             const float lam_init = 0.8f - 0.6f * expf(-0.3f * (float)l);
;             const float a1 = wave_sum(in[5][l * 64 + lane] * in[6][l * 64 + lane]), a2 = wave_sum(in[7][l * 64 + lane] * in[8][l * 64 + lane]);
;             const float lam = expf(a1) - expf(a2) + lam_init;
;             const float* sg = in[9] + l * 128 + (lane & 15) * 8; float gsc[8];
; #pragma unroll
;             for (int i = 0; i < 8; ++i) gsc[i] = sg[i] * (1.f - lam_init);
.LBB0_1636:
	s_or_b64 exec, exec, s[8:9]
	s_mov_b64 s[8:9], s[0:1]
	s_waitcnt lgkmcnt(0)
	s_barrier
	v_mbcnt_lo_u32_b32 v0, -1, 0
	v_mbcnt_hi_u32_b32 v0, -1, v0
	s_load_dwordx2 s[8:9], s[8:9], 0x28
	v_and_b32_e32 v2, 63, v0
	v_lshlrev_b32_e32 v1, 2, v2
	s_and_b64 vcc, exec, s[38:39]
	s_waitcnt lgkmcnt(0)
	global_load_dword v3, v1, s[8:9] offset:256
	s_mov_b64 s[8:9], s[0:1]
	s_load_dwordx2 s[8:9], s[8:9], 0x30
	s_waitcnt lgkmcnt(0)
	global_load_dword v4, v1, s[8:9] offset:256
	s_mov_b64 s[8:9], s[0:1]
	s_load_dwordx2 s[8:9], s[8:9], 0x38
	s_waitcnt lgkmcnt(0)
	global_load_dword v11, v1, s[8:9] offset:256
	s_mov_b64 s[8:9], s[0:1]
	s_load_dwordx2 s[8:9], s[8:9], 0x40
	s_waitcnt lgkmcnt(0)
	global_load_dword v1, v1, s[8:9] offset:256
	s_mov_b64 s[8:9], s[0:1]
	s_waitcnt vmcnt(2)
	v_mul_f32_e32 v18, v3, v4
	s_nop 1
	v_mov_b32_dpp v5, v18 quad_perm:[1,0,3,2] row_mask:0xf bank_mask:0xf
	v_fmac_f32_e32 v5, v3, v4
	s_nop 1
	v_mov_b32_dpp v3, v5 quad_perm:[2,3,0,1] row_mask:0xf bank_mask:0xf
	v_add_f32_e32 v3, v5, v3
	s_nop 1
	v_mov_b32_dpp v5, v3 row_shl:4 row_mask:0xf bank_mask:0x5
	v_mov_b32_dpp v5, v3 row_shr:4 row_mask:0xf bank_mask:0xa
	v_add_f32_e32 v3, v3, v5
	s_nop 1
	v_mov_b32_dpp v5, v3 row_ror:8 row_mask:0xf bank_mask:0xf
	s_waitcnt vmcnt(0)
	v_mul_f32_e32 v18, v11, v1
	s_nop 1
	v_mov_b32_dpp v12, v18 quad_perm:[1,0,3,2] row_mask:0xf bank_mask:0xf
	v_add_f32_e32 v3, v3, v5
	v_mov_b32_e32 v5, v3
	v_mov_b32_e32 v120, v3
	s_nop 1
	v_permlane16_swap_b32_e32 v5, v120
	v_cndmask_b32_e64 v5, v120, v5, s[98:99]
	v_fmac_f32_e32 v12, v11, v1
	s_nop 1
	v_mov_b32_dpp v1, v12 quad_perm:[2,3,0,1] row_mask:0xf bank_mask:0xf
	v_add_f32_e32 v1, v12, v1
	s_nop 1
	v_mov_b32_dpp v4, v1 row_shl:4 row_mask:0xf bank_mask:0x5
	v_mov_b32_dpp v4, v1 row_shr:4 row_mask:0xf bank_mask:0xa
	v_add_f32_e32 v1, v1, v4
	s_nop 1
	v_mov_b32_dpp v4, v1 row_ror:8 row_mask:0xf bank_mask:0xf
	v_add_f32_e32 v1, v1, v4
	v_mov_b32_e32 v6, v1
	v_mov_b32_e32 v120, v1
	s_nop 1
	v_permlane16_swap_b32_e32 v6, v120
	v_cndmask_b32_e64 v6, v120, v6, s[98:99]
	v_add_f32_e32 v4, v3, v5
	v_mov_b32_e32 v5, v4
	v_mov_b32_e32 v120, v4
	s_nop 1
	v_permlane32_swap_b32_e32 v5, v120
	v_cndmask_b32_e64 v5, v120, v5, s[100:101]
	v_add_f32_e32 v1, v1, v6
	v_mov_b32_e32 v3, v1
	v_mov_b32_e32 v120, v1
	s_nop 1
	v_permlane32_swap_b32_e32 v3, v120
	v_cndmask_b32_e64 v3, v120, v3, s[100:101]
	s_cbranch_vccz .LBB0_1639
	s_load_dwordx2 s[8:9], s[8:9], 0x48
	v_lshlrev_b32_e32 v0, 5, v0
	v_and_b32_e32 v0, 0x1e0, v0
	s_waitcnt lgkmcnt(0)
	v_add_f32_e32 v4, v4, v5
	v_add_f32_e32 v16, v1, v3
	global_load_dwordx4 v[6:9], v0, s[8:9] offset:512
	global_load_dwordx4 v[10:13], v0, s[8:9] offset:528
	s_mov_b32 s9, 0x3fb8aa3b
	v_mul_f32_e32 v3, 0x3fb8aa3b, v4
	v_mul_f32_e32 v17, 0x3fb8aa3b, v16
	v_fma_f32 v18, v4, s9, -v3
	v_rndne_f32_e32 v19, v3
	v_fma_f32 v20, v16, s9, -v17
	v_rndne_f32_e32 v21, v17
	v_fmac_f32_e32 v18, 0x32a5705f, v4
	v_sub_f32_e32 v3, v3, v19
	v_fmac_f32_e32 v20, 0x32a5705f, v16
	v_sub_f32_e32 v17, v17, v21
	v_add_f32_e32 v3, v3, v18
	v_cvt_i32_f32_e32 v19, v19
	v_add_f32_e32 v17, v17, v20
	v_exp_f32_e32 v18, v3
	v_cvt_i32_f32_e32 v21, v21
	v_exp_f32_e32 v17, v17
	s_mov_b32 s19, 0xc2ce8ed0
	v_ldexp_f32 v18, v18, v19
	v_cmp_ngt_f32_e32 vcc, s19, v4
	s_mov_b32 s20, 0x42b17218
	v_ldexp_f32 v17, v17, v21
	v_cndmask_b32_e32 v18, 0, v18, vcc
	v_cmp_ngt_f32_e32 vcc, s19, v16
	v_mov_b32_e32 v5, 0x7f800000
	s_ashr_i32 s35, s34, 31
	v_cndmask_b32_e32 v17, 0, v17, vcc
	v_cmp_nlt_f32_e32 vcc, s20, v4
	s_lshl_b64 s[14:15], s[34:35], 10
	s_mov_b32 s8, 0x3f24fd5c
	v_cndmask_b32_e32 v4, v5, v18, vcc
	v_cmp_nlt_f32_e32 vcc, s20, v16
	v_lshlrev_b32_e32 v0, 3, v2
	s_mov_b64 s[12:13], 0x20500000
	v_cndmask_b32_e32 v5, v5, v17, vcc
	v_sub_f32_e32 v4, v4, v5
	s_ashr_i32 s31, s30, 31
	v_lshl_or_b32 v2, v2, 4, s14
	v_mov_b32_e32 v3, s15
	v_add_f32_e32 v4, 0x3eb60549, v4
	v_mov_b32_e32 v1, 0
	s_mov_b32 s3, 0x20500000
	s_mov_b32 s16, 0xffff0000
	v_mov_b32_e32 v14, 0x3727c5ac
	s_mov_b32 s17, 0xf800000
	v_mov_b32_e32 v15, 0x260
	s_movk_i32 s18, 0x7fff
	s_lshl_b64 s[10:11], s[30:31], 10
	v_lshlrev_b32_e32 v0, 1, v0
	v_lshl_add_u64 v[2:3], v[2:3], 0, s[12:13]
	v_mov_b32_e32 v5, v4
	s_mov_b32 s19, s34
	s_waitcnt vmcnt(1)
	v_mov_b32_e32 v16, v6
	v_mov_b32_e32 v17, v8
	v_mov_b32_e32 v8, v7
	s_waitcnt vmcnt(0)
	v_mov_b32_e32 v18, v10
	v_mov_b32_e32 v19, v12
	v_mov_b32_e32 v12, v11
	v_pk_mul_f32 v[6:7], v[16:17], s[8:9] op_sel_hi:[1,0]
	v_pk_mul_f32 v[8:9], v[8:9], s[8:9] op_sel_hi:[1,0]
	v_pk_mul_f32 v[10:11], v[18:19], s[8:9] op_sel_hi:[1,0]
	v_pk_mul_f32 v[12:13], v[12:13], s[8:9] op_sel_hi:[1,0]
; __device__ __forceinline__ float shx(float v, int o) { const int l = lane_now(); return __int_as_float(__builtin_amdgcn_ds_bpermute((l ^ o) << 2, __float_as_int(v))); }
; __device__ __forceinline__ float bf_lo(unsigned w) { return __uint_as_float(w << 16); }
; __device__ __forceinline__ float bf_hi(unsigned w) { return __uint_as_float(w & 0xffff0000u); }
; __device__ __forceinline__ unsigned pk2(float lo, float hi) { return f2bf(lo) | (f2bf(hi) << 16); }
; template <int l, int SEL> __device__ __forceinline__ void layer_body(const Args& args, LAS unsigned char* ldsp, unsigned char* lds, const int G, const int bx, const int vcu, const int wv) {
;     ...
;             for (int row = gw; row < M; row += NGW) {
;                 const v4u a = *(const v4u*)(q_odiff + (size_t)row * 512 + 8 * lane), b = *(const v4u*)(q_odiff + (size_t)(M + row) * 512 + 8 * lane);
;                 float o[8]; const unsigned aw[4] = {a.x, a.y, a.z, a.w}, bw[4] = {b.x, b.y, b.z, b.w};
; #pragma unroll
;                 for (int i = 0; i < 4; ++i) { o[2 * i] = pg8::bf_lo(aw[i]) - lam * pg8::bf_lo(bw[i]); o[2 * i + 1] = pg8::bf_hi(aw[i]) - lam * pg8::bf_hi(bw[i]); }
;                 float ss = 0.f;
; #pragma unroll
;                 for (int i = 0; i < 8; ++i) ss += o[i] * o[i];
;                 ss += shx(ss, 1); ss += shx(ss, 2); ss += shx(ss, 4); ss += shx(ss, 8);
;                 const float r = 1.f / sqrtf(ss * (1.f / 128.f) + SUBLN_EPS);
;                 v4u w; w.x = pk2(o[0] * r * gsc[0], o[1] * r * gsc[1]); w.y = pk2(o[2] * r * gsc[2], o[3] * r * gsc[3]); w.z = pk2(o[4] * r * gsc[4], o[5] * r * gsc[5]); w.w = pk2(o[6] * r * gsc[6], o[7] * r * gsc[7]);
;                 *(v4u*)(q_yatt + (size_t)(M + row) * 512 + 8 * lane) = w;
;             }
.LBB0_1638:
	s_mov_b64 s[12:13], s[0:1]
	s_load_dwordx2 s[12:13], s[12:13], 0xc0
	s_mov_b64 s[8:9], s[0:1]
	s_add_i32 s14, s19, 0x4000
	s_ashr_i32 s15, s14, 31
	s_lshl_b64 s[14:15], s[14:15], 10
	s_waitcnt lgkmcnt(0)
	v_lshl_add_u64 v[16:17], s[12:13], 0, v[2:3]
	global_load_dwordx4 v[16:19], v[16:17], off
	s_load_dwordx2 s[8:9], s[8:9], 0xc0
	s_mov_b64 s[20:21], s[0:1]
	v_lshl_add_u64 v[2:3], v[2:3], 0, s[10:11]
	s_waitcnt lgkmcnt(0)
	s_add_u32 s8, s8, s14
	s_addc_u32 s9, s9, s15
	v_lshl_add_u64 v[20:21], s[8:9], 0, v[0:1]
	v_add_co_u32_e32 v20, vcc, s3, v20
	s_nop 1
	v_addc_co_u32_e32 v21, vcc, 0, v21, vcc
	global_load_dwordx4 v[20:23], v[20:21], off
	s_waitcnt vmcnt(1)
	v_lshlrev_b32_e32 v29, 16, v19
	v_mbcnt_lo_u32_b32 v24, -1, 0
	v_mbcnt_hi_u32_b32 v24, -1, v24
	v_mbcnt_lo_u32_b32 v25, -1, 0
	v_mbcnt_hi_u32_b32 v25, -1, v25
	v_mbcnt_lo_u32_b32 v26, -1, 0
	v_mbcnt_hi_u32_b32 v26, -1, v26
	v_mbcnt_lo_u32_b32 v27, -1, 0
	v_mbcnt_hi_u32_b32 v27, -1, v27
	v_lshlrev_b32_e32 v28, 16, v18
	v_lshlrev_b32_e32 v26, 2, v26
	v_lshlrev_b32_e32 v27, 2, v27
	v_xor_b32_e32 v36, 16, v26
	v_xor_b32_e32 v37, 32, v27
	v_lshlrev_b32_e32 v27, 16, v17
	v_lshlrev_b32_e32 v26, 16, v16
	v_and_b32_e32 v17, 0xffff0000, v17
	v_and_b32_e32 v16, 0xffff0000, v16
	v_and_b32_e32 v19, 0xffff0000, v19
	v_and_b32_e32 v18, 0xffff0000, v18
	v_lshlrev_b32_e32 v24, 2, v24
	v_xor_b32_e32 v34, 4, v24
	v_lshlrev_b32_e32 v25, 2, v25
	v_xor_b32_e32 v35, 8, v25
	s_load_dwordx2 s[8:9], s[20:21], 0xc0
	s_waitcnt lgkmcnt(0)
	s_add_u32 s8, s8, s14
	s_addc_u32 s9, s9, s15
	v_lshl_add_u64 v[24:25], s[8:9], 0, v[0:1]
	s_add_i32 s19, s19, s30
	s_cmpk_gt_i32 s19, 0x3fff
	s_waitcnt vmcnt(0)
	v_lshlrev_b32_e32 v31, 16, v21
	v_lshlrev_b32_e32 v30, 16, v20
	v_and_b32_e32 v21, 0xffff0000, v21
	v_and_b32_e32 v20, 0xffff0000, v20
	v_lshlrev_b32_e32 v33, 16, v23
	v_lshlrev_b32_e32 v32, 16, v22
	v_and_b32_e32 v23, 0xffff0000, v23
	v_and_b32_e32 v22, 0xffff0000, v22
	v_pk_fma_f32 v[26:27], v[4:5], v[30:31], v[26:27] neg_lo:[1,0,0] neg_hi:[1,0,0]
	v_pk_fma_f32 v[16:17], v[4:5], v[20:21], v[16:17] neg_lo:[1,0,0] neg_hi:[1,0,0]
	v_pk_fma_f32 v[20:21], v[4:5], v[32:33], v[28:29] neg_lo:[1,0,0] neg_hi:[1,0,0]
	v_pk_fma_f32 v[18:19], v[4:5], v[22:23], v[18:19] neg_lo:[1,0,0] neg_hi:[1,0,0]
	v_pk_mul_f32 v[22:23], v[26:27], v[26:27]
	v_pk_mul_f32 v[28:29], v[16:17], v[16:17]
	v_mov_b32_e32 v30, v18
	v_add_f32_e32 v22, v22, v28
	v_mov_b32_e32 v31, v20
	v_add_f32_e32 v22, v23, v22
	v_pk_mul_f32 v[30:31], v[30:31], v[30:31]
	v_add_f32_e32 v22, v29, v22
	v_mov_b32_e32 v32, v19
	v_mov_b32_e32 v33, v21
	v_add_f32_e32 v22, v31, v22
	v_pk_mul_f32 v[32:33], v[32:33], v[32:33]
	v_add_f32_e32 v22, v30, v22
	v_add_f32_e32 v22, v33, v22
	v_add_f32_e32 v22, v32, v22
	s_nop 1
	v_mov_b32_dpp v23, v22 quad_perm:[1,0,3,2] row_mask:0xf bank_mask:0xf
	v_add_f32_e32 v22, v22, v23
	s_nop 1
	v_mov_b32_dpp v23, v22 quad_perm:[2,3,0,1] row_mask:0xf bank_mask:0xf
	v_add_f32_e32 v22, v22, v23
	s_nop 1
	v_mov_b32_dpp v23, v22 row_shl:4 row_mask:0xf bank_mask:0x5
	v_mov_b32_dpp v23, v22 row_shr:4 row_mask:0xf bank_mask:0xa
	v_add_f32_e32 v22, v22, v23
	s_nop 1
	v_mov_b32_dpp v23, v22 row_ror:8 row_mask:0xf bank_mask:0xf
	v_add_f32_e32 v22, v22, v23
	v_fmamk_f32 v22, v22, 0x3c000000, v14
	v_mul_f32_e32 v23, 0x4f800000, v22
	v_cmp_gt_f32_e32 vcc, s17, v22
	s_nop 1
	v_cndmask_b32_e32 v22, v22, v23, vcc
	v_sqrt_f32_e32 v23, v22
	s_nop 0
	v_add_u32_e32 v28, -1, v23
	v_add_u32_e32 v29, 1, v23
	v_fma_f32 v30, -v28, v23, v22
	v_fma_f32 v31, -v29, v23, v22
	v_cmp_ge_f32_e64 s[8:9], 0, v30
	s_nop 1
	v_cndmask_b32_e64 v23, v23, v28, s[8:9]
	v_cmp_lt_f32_e64 s[8:9], 0, v31
	s_nop 1
	v_cndmask_b32_e64 v23, v23, v29, s[8:9]
	v_mul_f32_e32 v28, 0x37800000, v23
	v_cndmask_b32_e32 v23, v23, v28, vcc
	v_cmp_class_f32_e32 vcc, v22, v15
	s_nop 1
	v_cndmask_b32_e32 v23, v23, v22, vcc
	v_div_scale_f32 v22, s[8:9], v23, v23, 1.0
	v_rcp_f32_e32 v29, v22
	v_div_scale_f32 v28, vcc, 1.0, v23, 1.0
	v_fma_f32 v30, -v22, v29, 1.0
	v_fmac_f32_e32 v29, v30, v29
	v_mul_f32_e32 v30, v28, v29
	v_fma_f32 v31, -v22, v30, v28
	v_fmac_f32_e32 v30, v31, v29
	v_fma_f32 v22, -v22, v30, v28
	v_div_fmas_f32 v28, v22, v29, v30
	v_add_co_u32_e32 v22, vcc, 0x1e500000, v24
	v_div_fixup_f32 v24, v28, v23, 1.0
	v_pk_mul_f32 v[26:27], v[26:27], v[24:25] op_sel_hi:[1,0]
	v_pk_mul_f32 v[20:21], v[20:21], v[24:25] op_sel_hi:[1,0]
	v_addc_co_u32_e32 v23, vcc, 0, v25, vcc
	v_pk_mul_f32 v[16:17], v[16:17], v[24:25] op_sel_hi:[1,0]
	v_pk_mul_f32 v[18:19], v[18:19], v[24:25] op_sel_hi:[1,0]
	v_pk_mul_f32 v[24:25], v[6:7], v[26:27]
	v_pk_mul_f32 v[20:21], v[10:11], v[20:21]
	v_pk_mul_f32 v[16:17], v[8:9], v[16:17]
	v_pk_mul_f32 v[18:19], v[12:13], v[18:19]
	v_bfe_u32 v30, v24, 16, 1
	v_bfe_u32 v31, v25, 16, 1
	v_bfe_u32 v32, v20, 16, 1
	v_bfe_u32 v33, v21, 16, 1
	v_bfe_u32 v26, v19, 16, 1
	v_bfe_u32 v27, v18, 16, 1
	v_bfe_u32 v28, v17, 16, 1
	v_bfe_u32 v29, v16, 16, 1
	v_add3_u32 v21, v21, v33, s18
	v_add3_u32 v20, v20, v32, s18
	v_add3_u32 v25, v25, v31, s18
	v_add3_u32 v24, v24, v30, s18
	v_add3_u32 v16, v16, v29, s18
	v_add3_u32 v17, v17, v28, s18
	v_add3_u32 v18, v18, v27, s18
	v_add3_u32 v19, v19, v26, s18
	v_lshrrev_b32_e32 v24, 16, v24
	v_lshrrev_b32_e32 v25, 16, v25
	v_lshrrev_b32_e32 v20, 16, v20
	v_lshrrev_b32_e32 v21, 16, v21
	v_and_or_b32 v19, v19, s16, v21
	v_and_or_b32 v18, v18, s16, v20
	v_and_or_b32 v17, v17, s16, v25
	v_and_or_b32 v16, v16, s16, v24
	global_store_dwordx4 v[22:23], v[16:19], off
	s_cbranch_scc0 .LBB0_1638

; template <int SRC, int EXTRA, bool OUT8 = false> ...
;     ...
;             const int p0 = pos[2 * row], p1 = pos[2 * row + 1]; const float w0 = gwt[2 * row], w1 = gwt[2 * row + 1]; const float hm = hp.stats[2 * row], hr = hp.stats[2 * row + 1];
; #pragma unroll
;             for (int j = 0; j < 4; ++j) { const f32x4 a = (*(const f32x4*)(hp.src + (size_t)row * 1024 + 256 * j + 4 * lane) - hm) * hr * *(const f32x4*)(hp.g + 256 * j + 4 * lane) + *(const f32x4*)(hp.b + 256 * j + 4 * lane);
;                 f32x4 y[2];
; #pragma unroll
;                 for (int q = 0; q < 2; ++q) { const int p = q ? p1 : p0; const int t = __builtin_amdgcn_readfirstlane(tailid[(p >> 8) * 4 + j]);
;                     if (t < 0) y[q] = *(const f32x4*)(ys + (size_t)p * 1024 + 256 * j + 4 * lane);
;                     else { f32x4 acc = (f32x4){0.f, 0.f, 0.f, 0.f};
; #pragma unroll
;                         for (int sl = 0; sl < 7; ++sl) acc = acc + *(const f32x4*)(part + ((size_t)(t * 7 + sl) * 256 + (p & 255)) * 256 + 4 * lane);
;                         y[q] = acc; } }
;                 v[j] = a * ALPHA + y[0] * w0 + y[1] * w1; }
;         }
;         float s = 0.f;
; #pragma unroll
;         for (int j = 0; j < 4; ++j) s += (v[j].x + v[j].y) + (v[j].z + v[j].w);
;         const float mean = wave_sum(s) * (1.f / 1024.f); float s2 = 0.f;
; #pragma unroll
;         for (int j = 0; j < 4; ++j) { v[j] = v[j] - mean; s2 += (v[j].x * v[j].x + v[j].y * v[j].y) + (v[j].z * v[j].z + v[j].w * v[j].w); }
;         const float rstd = 1.f / sqrtf(wave_sum(s2) * (1.f / 1024.f) + LN_EPS);
.LBB0_2278:
	v_sub_f32_e32 v83, v83, v124
	v_sub_f32_e32 v82, v82, v124
	v_sub_f32_e32 v81, v81, v124
	v_sub_f32_e32 v80, v80, v124
	v_pk_mul_f32 v[80:81], v[124:125], v[80:81] op_sel:[1,0]
	v_pk_mul_f32 v[82:83], v[124:125], v[82:83] op_sel:[1,0]
	v_sub_f32_e32 v43, v43, v124
	v_sub_f32_e32 v42, v42, v124
	v_sub_f32_e32 v41, v41, v124
	v_sub_f32_e32 v40, v40, v124
	v_pk_fma_f32 v[74:75], v[74:75], v[82:83], v[78:79]
	v_pk_fma_f32 v[72:73], v[72:73], v[80:81], v[76:77]
	v_pk_mul_f32 v[78:79], v[122:123], v[84:85] op_sel_hi:[0,1]
	v_pk_mul_f32 v[40:41], v[124:125], v[40:41] op_sel:[1,0]
	v_pk_mul_f32 v[42:43], v[124:125], v[42:43] op_sel:[1,0]
	v_pk_mul_f32 v[76:77], v[122:123], v[86:87] op_sel_hi:[0,1]
	v_pk_fma_f32 v[78:79], v[72:73], s[14:15], v[78:79] op_sel_hi:[1,0,1]
	v_pk_fma_f32 v[34:35], v[34:35], v[42:43], v[38:39]
	v_pk_fma_f32 v[32:33], v[32:33], v[40:41], v[36:37]
	v_pk_mul_f32 v[38:39], v[122:123], v[44:45] op_sel_hi:[0,1]
	v_pk_fma_f32 v[72:73], v[74:75], s[14:15], v[76:77] op_sel_hi:[1,0,1]
	v_pk_fma_f32 v[74:75], v[122:123], v[96:97], v[78:79] op_sel:[1,0,0]
	v_sub_f32_e32 v79, v101, v124
	v_sub_f32_e32 v78, v100, v124
	v_sub_f32_e32 v63, v63, v124
	v_sub_f32_e32 v62, v62, v124
	v_sub_f32_e32 v61, v61, v124
	v_sub_f32_e32 v60, v60, v124
	v_pk_mul_f32 v[36:37], v[122:123], v[46:47] op_sel_hi:[0,1]
	v_pk_fma_f32 v[32:33], v[32:33], s[14:15], v[38:39] op_sel_hi:[1,0,1]
	v_sub_f32_e32 v77, v103, v124
	v_sub_f32_e32 v76, v102, v124
	v_pk_mul_f32 v[60:61], v[124:125], v[60:61] op_sel:[1,0]
	v_pk_mul_f32 v[62:63], v[124:125], v[62:63] op_sel:[1,0]
	v_pk_fma_f32 v[34:35], v[34:35], s[14:15], v[36:37] op_sel_hi:[1,0,1]
	v_pk_fma_f32 v[38:39], v[122:123], v[48:49], v[32:33] op_sel:[1,0,0]
	v_pk_mul_f32 v[32:33], v[124:125], v[78:79] op_sel:[1,0]
	v_pk_fma_f32 v[54:55], v[54:55], v[62:63], v[58:59]
	v_pk_fma_f32 v[52:53], v[52:53], v[60:61], v[56:57]
	v_pk_mul_f32 v[56:57], v[122:123], v[66:67] op_sel_hi:[0,1]
	v_pk_mul_f32 v[58:59], v[122:123], v[64:65] op_sel_hi:[0,1]
	v_pk_fma_f32 v[36:37], v[122:123], v[50:51], v[34:35] op_sel:[1,0,0]
	v_pk_mul_f32 v[34:35], v[124:125], v[76:77] op_sel:[1,0]
	v_pk_fma_f32 v[32:33], v[88:89], v[32:33], v[92:93]
	v_pk_mul_f32 v[42:43], v[122:123], v[104:105] op_sel_hi:[0,1]
	v_pk_fma_f32 v[58:59], v[52:53], s[14:15], v[58:59] op_sel_hi:[1,0,1]
	v_pk_fma_f32 v[52:53], v[54:55], s[14:15], v[56:57] op_sel_hi:[1,0,1]
	v_pk_fma_f32 v[34:35], v[90:91], v[34:35], v[94:95]
	v_pk_mul_f32 v[40:41], v[122:123], v[106:107] op_sel_hi:[0,1]
	v_pk_fma_f32 v[42:43], v[32:33], s[14:15], v[42:43] op_sel_hi:[1,0,1]
	v_pk_fma_f32 v[52:53], v[122:123], v[70:71], v[52:53] op_sel:[1,0,0]
	v_pk_fma_f32 v[54:55], v[122:123], v[68:69], v[58:59] op_sel:[1,0,0]
	v_pk_fma_f32 v[32:33], v[34:35], s[14:15], v[40:41] op_sel_hi:[1,0,1]
	s_waitcnt vmcnt(0)
	v_pk_fma_f32 v[34:35], v[122:123], v[108:109], v[42:43] op_sel:[1,0,0]
	v_pk_mov_b32 v[40:41], v[38:39], v[36:37] op_sel:[1,0]
	v_mov_b32_e32 v42, v38
	v_mov_b32_e32 v43, v37
	v_pk_add_f32 v[40:41], v[40:41], v[42:43]
	v_pk_mov_b32 v[42:43], v[54:55], v[52:53] op_sel:[1,0]
	v_mov_b32_e32 v44, v54
	v_mov_b32_e32 v45, v53
	v_pk_add_f32 v[42:43], v[42:43], v[44:45]
	v_pk_fma_f32 v[72:73], v[122:123], v[98:99], v[72:73] op_sel:[1,0,0]
	v_pk_fma_f32 v[32:33], v[122:123], v[110:111], v[32:33] op_sel:[1,0,0]
	v_add_f32_e32 v40, v40, v41
	v_pk_add_f32 v[42:43], v[42:43], v[42:43] op_sel:[0,1] op_sel_hi:[1,0]
	v_add_f32_e32 v40, 0, v40
	v_add_f32_e32 v44, v74, v75
	v_add_f32_e32 v46, v72, v73
	v_mov_b32_e32 v41, v34
	v_mov_b32_e32 v43, v35
	v_mov_b32_e32 v45, v32
	v_mov_b32_e32 v47, v33
	v_pk_add_f32 v[40:41], v[40:41], v[42:43]
	v_pk_add_f32 v[42:43], v[44:45], v[46:47]
	s_andn2_b64 vcc, exec, s[4:5]
	v_pk_add_f32 v[40:41], v[40:41], v[42:43]
	s_nop 0
	v_add_f32_e32 v40, v40, v41
	s_nop 0
	s_nop 1
	v_mov_b32_dpp v41, v40 quad_perm:[1,0,3,2] row_mask:0xf bank_mask:0xf
	v_add_f32_e32 v40, v40, v41
	s_nop 0
	s_nop 1
	v_mov_b32_dpp v41, v40 quad_perm:[2,3,0,1] row_mask:0xf bank_mask:0xf
	v_add_f32_e32 v40, v40, v41
	s_nop 0
	s_nop 1
	v_mov_b32_dpp v41, v40 row_shl:4 row_mask:0xf bank_mask:0x5
	v_mov_b32_dpp v41, v40 row_shr:4 row_mask:0xf bank_mask:0xa
	v_add_f32_e32 v40, v40, v41
	s_nop 0
	s_nop 1
	v_mov_b32_dpp v41, v40 row_ror:8 row_mask:0xf bank_mask:0xf
	v_add_f32_e32 v40, v40, v41
	s_nop 0
	v_mov_b32_e32 v41, v40
	v_mov_b32_e32 v200, v40
	s_nop 1
	v_permlane16_swap_b32_e32 v41, v200
	v_cndmask_b32_e64 v41, v200, v41, s[98:99]
	v_add_f32_e32 v40, v40, v41
	s_nop 0
	v_mov_b32_e32 v41, v40
	v_mov_b32_e32 v200, v40
	s_nop 1
	v_permlane32_swap_b32_e32 v41, v200
	v_cndmask_b32_e64 v41, v200, v41, s[100:101]
	v_add_f32_e32 v40, v40, v41
	v_fmamk_f32 v37, v40, 0xba800000, v37
	v_fmamk_f32 v39, v40, 0xba800000, v39
	v_fmac_f32_e32 v36, 0xba800000, v40
	v_fmac_f32_e32 v38, 0xba800000, v40
	v_mul_f32_e32 v41, v39, v39
	v_mul_f32_e32 v42, v37, v37
	v_fmac_f32_e32 v41, v38, v38
	v_fmac_f32_e32 v42, v36, v36
	v_fmamk_f32 v53, v40, 0xba800000, v53
	v_fmamk_f32 v55, v40, 0xba800000, v55
	v_add_f32_e32 v41, v41, v42
	v_fmac_f32_e32 v52, 0xba800000, v40
	v_fmac_f32_e32 v54, 0xba800000, v40
	v_mul_f32_e32 v42, v55, v55
	v_mul_f32_e32 v43, v53, v53
	v_fmac_f32_e32 v42, v54, v54
	v_fmac_f32_e32 v43, v52, v52
	v_add_f32_e32 v42, v42, v43
	v_fmamk_f32 v73, v40, 0xba800000, v73
	v_fmamk_f32 v75, v40, 0xba800000, v75
	v_add_f32_e32 v41, v41, v42
	v_fmac_f32_e32 v72, 0xba800000, v40
	v_fmac_f32_e32 v74, 0xba800000, v40
	v_mul_f32_e32 v42, v75, v75
	v_mul_f32_e32 v43, v73, v73
	v_fmac_f32_e32 v42, v74, v74
	v_fmac_f32_e32 v43, v72, v72
	v_add_f32_e32 v42, v42, v43
	v_fmamk_f32 v33, v40, 0xba800000, v33
	v_fmamk_f32 v35, v40, 0xba800000, v35
	v_add_f32_e32 v41, v42, v41
	v_fmac_f32_e32 v32, 0xba800000, v40
	v_fmac_f32_e32 v34, 0xba800000, v40
	v_mul_f32_e32 v40, v35, v35
	v_mul_f32_e32 v42, v33, v33
	v_fmac_f32_e32 v40, v34, v34
	v_fmac_f32_e32 v42, v32, v32
	v_add_f32_e32 v40, v40, v42
	v_add_f32_e32 v40, v40, v41
	s_nop 0
	s_nop 1
	v_mov_b32_dpp v41, v40 quad_perm:[1,0,3,2] row_mask:0xf bank_mask:0xf
	v_add_f32_e32 v40, v40, v41
	s_nop 0
	s_nop 1
	v_mov_b32_dpp v41, v40 quad_perm:[2,3,0,1] row_mask:0xf bank_mask:0xf
	v_add_f32_e32 v40, v40, v41
	s_nop 0
	s_nop 1
	v_mov_b32_dpp v41, v40 row_shl:4 row_mask:0xf bank_mask:0x5
	v_mov_b32_dpp v41, v40 row_shr:4 row_mask:0xf bank_mask:0xa
	v_add_f32_e32 v40, v40, v41
	s_nop 0
	s_nop 1
	v_mov_b32_dpp v41, v40 row_ror:8 row_mask:0xf bank_mask:0xf
	v_add_f32_e32 v40, v40, v41
	s_nop 0
	v_mov_b32_e32 v41, v40
	v_mov_b32_e32 v200, v40
	s_nop 1
	v_permlane16_swap_b32_e32 v41, v200
	v_cndmask_b32_e64 v41, v200, v41, s[98:99]
	v_add_f32_e32 v40, v40, v41
	s_nop 0
	v_mov_b32_e32 v41, v40
	v_mov_b32_e32 v200, v40
	s_nop 1
	v_permlane32_swap_b32_e32 v41, v200
	v_cndmask_b32_e64 v41, v200, v41, s[100:101]
	s_cbranch_vccnz .LBB0_2245
; template <int SRC, int EXTRA, bool OUT8 = false> ...
;     ...
;         const float rstd = 1.f / sqrtf(wave_sum(s2) * (1.f / 1024.f) + LN_EPS);
;         if (stats && lane == 0) { stats[2 * row] = mean; stats[2 * row + 1] = rstd; }
; #pragma unroll
;         for (int j = 0; j < 4; ++j) { v[j] = v[j] * rstd * gv[j] + bv[j]; if (of32) *(f32x4*)(of32 + (size_t)row * 1024 + 256 * j + 4 * lane) = v[j];
	v_add_f32_e32 v40, v40, v41
	v_fmamk_f32 v40, v40, 0x3a800000, v126
	v_mul_f32_e32 v41, 0x4f800000, v40
	v_cmp_gt_f32_e32 vcc, s33, v40
	s_nop 1
	v_cndmask_b32_e32 v40, v40, v41, vcc
	v_sqrt_f32_e32 v41, v40
	s_nop 0
	v_add_u32_e32 v42, -1, v41
	v_fma_f32 v44, -v42, v41, v40
	v_add_u32_e32 v43, 1, v41
	v_cmp_ge_f32_e64 s[0:1], 0, v44
	s_nop 1
	v_cndmask_b32_e64 v42, v41, v42, s[0:1]
	v_fma_f32 v41, -v43, v41, v40
	v_cmp_lt_f32_e64 s[0:1], 0, v41
	s_nop 1
	v_cndmask_b32_e64 v41, v42, v43, s[0:1]
	v_mul_f32_e32 v42, 0x37800000, v41
	v_cndmask_b32_e32 v41, v41, v42, vcc
	v_cmp_class_f32_e32 vcc, v40, v127
	s_nop 1
	v_cndmask_b32_e32 v42, v41, v40, vcc
	v_div_scale_f32 v43, s[0:1], v42, v42, 1.0
	v_rcp_f32_e32 v44, v43
	v_lshl_add_u64 v[40:41], s[12:13], 0, v[112:113]
	v_fma_f32 v45, -v43, v44, 1.0
	v_fmac_f32_e32 v44, v45, v44
	v_div_scale_f32 v45, vcc, 1.0, v42, 1.0
	v_mul_f32_e32 v46, v45, v44
	v_fma_f32 v47, -v43, v46, v45
	v_fmac_f32_e32 v46, v47, v44
	v_fma_f32 v43, -v43, v46, v45
	v_div_fmas_f32 v43, v43, v44, v46
	v_div_fixup_f32 v42, v43, v42, 1.0
	v_pk_mul_f32 v[44:45], v[38:39], v[42:43] op_sel_hi:[1,0]
	v_pk_mul_f32 v[36:37], v[36:37], v[42:43] op_sel_hi:[1,0]
	v_pk_mul_f32 v[32:33], v[32:33], v[42:43] op_sel_hi:[1,0]
	v_pk_fma_f32 v[38:39], v[2:3], v[36:37], v[6:7]
	v_pk_fma_f32 v[36:37], v[0:1], v[44:45], v[4:5]
	global_store_dwordx4 v[40:41], v[36:39], off
	s_nop 1
	v_pk_mul_f32 v[36:37], v[54:55], v[42:43] op_sel_hi:[1,0]
	v_pk_mul_f32 v[38:39], v[52:53], v[42:43] op_sel_hi:[1,0]
	v_pk_fma_f32 v[36:37], v[8:9], v[36:37], v[16:17]
	v_pk_fma_f32 v[38:39], v[10:11], v[38:39], v[18:19]
	global_store_dwordx4 v[40:41], v[36:39], off offset:1024
	s_nop 1
	v_pk_mul_f32 v[36:37], v[74:75], v[42:43] op_sel_hi:[1,0]
	v_pk_mul_f32 v[38:39], v[72:73], v[42:43] op_sel_hi:[1,0]
	v_pk_fma_f32 v[36:37], v[12:13], v[36:37], v[20:21]
	v_pk_fma_f32 v[38:39], v[14:15], v[38:39], v[22:23]
	global_store_dwordx4 v[40:41], v[36:39], off offset:2048
	s_nop 1
	v_pk_mul_f32 v[36:37], v[34:35], v[42:43] op_sel_hi:[1,0]
	v_pk_fma_f32 v[34:35], v[26:27], v[32:33], v[30:31]
	v_pk_fma_f32 v[32:33], v[24:25], v[36:37], v[28:29]
	global_store_dwordx4 v[40:41], v[32:35], off offset:3072
	s_branch .LBB0_2245
